# GEMM: first K-iteration of each unit peeled with C=0 MFMAs, accumulator zeroing removed
# speedup vs baseline: 1.0071x; 1.0045x over previous
; #define PG8_WAIT_V(n) asm volatile("s_waitcnt vmcnt(" #n ")" ::: "memory")
; #define PG8_WAIT_L(n) asm volatile("s_waitcnt lgkmcnt(" #n ")" ::: "memory")
; template <class Epi>
; DI void gemm_phase(LAS unsigned char* lds, const Gemm g, const Epi& E) {
;     ...
;   f32x4 acc[2][2][4][2];
; #pragma unroll
;   for (int a = 0; a < 2; ++a)
; #pragma unroll
;     for (int b = 0; b < 2; ++b)
; #pragma unroll
;       for (int m = 0; m < 4; ++m)
; #pragma unroll
;         for (int n = 0; n < 2; ++n) acc[a][b][m][n] = (f32x4){0.f, 0.f, 0.f, 0.f};
;   bf16x8 At[4][2], B0[2][2], B1[2][2];
;     ...
;   const char* cA = PG8_APTR(cur); const char* cB = (const char*)g.Bt + (size_t)cur.pn * tstepB;
;   PG8_STAGE(PG8_SB(0, 0), cB, voffB); PG8_STAGE(PG8_SA(0, 0), cA, voffA); PG8_STAGE(PG8_SB(0, 1), cB + hstepB, voffB); PG8_STAGE(PG8_SA(0, 1), cA + hstepA, voffA);
;   if (wr == 1) PG8_BAR;
;   PG8_WAIT_V(4); PG8_BAR;
;   PG8_STAGE(PG8_SB(1, 0), cB + kstep, voffB); PG8_STAGE(PG8_SA(1, 0), cA + kstep, voffA); PG8_STAGE(PG8_SB(1, 1), cB + hstepB + kstep, voffB);
;   PG8_WAIT_V(6); PG8_BAR;
;   for (;;) {
;     const bool has_next = S.next(ui + 1, nxt);
;     const char* nA = has_next ? PG8_APTR(nxt) : cA; const char* nB = has_next ? (const char*)g.Bt + (size_t)nxt.pn * tstepB : cB;
;     for (int t = 0; t < nt; t += 2) {
;       const bool last = (t == nt - 2);
;       const char* a1 = cA + (size_t)(t + 1) * kstep;
;       const char* a2 = last ? nA : cA + (size_t)(t + 2) * kstep; const char* b2 = last ? nB : cB + (size_t)(t + 2) * kstep;
;       const char* a3 = a2 + kstep; const char* b3 = b2 + kstep;
;       PG8_LDB(B0, 0, 0); PG8_SCHED; PG8_LDA(At, 0, 0); PG8_STAGE(PG8_SA(1, 1), a1 + hstepA, voffA);
;       PG8_WAIT_L(8); PG8_BAR; PG8_WAIT_L(0); PG8_MMA(0, 0, At, B0); PG8_BAR; PG8_SCHED;
;       PG8_LDB(B1, 0, 1); PG8_STAGE(PG8_SB(0, 0), b2, voffB);
;       PG8_BAR; PG8_WAIT_L(0); PG8_MMA(0, 1, At, B1); PG8_BAR;
;       PG8_LDA(At, 0, 1); PG8_STAGE(PG8_SA(0, 0), a2, voffA);
;       PG8_BAR; PG8_WAIT_L(0); PG8_MMA(1, 0, At, B0); PG8_BAR; PG8_SCHED;
;       PG8_STAGE(PG8_SB(0, 1), b2 + hstepB, voffB);
;       PG8_WAIT_V(6); PG8_BAR; PG8_MMA(1, 1, At, B1); PG8_BAR;
;       PG8_LDB(B0, 1, 0); PG8_SCHED; PG8_LDA(At, 1, 0); PG8_STAGE(PG8_SA(0, 1), a2 + hstepA, voffA);
;       PG8_WAIT_L(8); PG8_BAR; PG8_WAIT_L(0); PG8_MMA(0, 0, At, B0); PG8_BAR; PG8_SCHED;
.LBB0_189:
	s_ashr_i32 s13, s12, 31
	v_cmp_lt_i64_e32 vcc, s[18:19], v[170:171]
	s_lshl_b64 s[18:19], s[12:13], 20
	s_add_u32 s18, s42, s18
	s_addc_u32 s19, s43, s19
	s_and_b64 s[22:23], vcc, exec
	s_cselect_b32 s13, s19, s31
	s_cselect_b32 s55, s18, s30
	s_ashr_i32 s3, s2, 31
	s_lshl_b64 s[22:23], s[2:3], 20
	s_add_u32 s22, s44, s22
	s_addc_u32 s23, s45, s23
	s_and_b64 s[40:41], vcc, exec
	s_cselect_b32 s3, s23, s37
	s_cselect_b32 s56, s22, s36
	s_add_u32 s30, s30, 0x80080
	s_addc_u32 s31, s31, 0
	s_add_u32 s57, s36, 0x100
	s_addc_u32 s58, s37, 0
	s_mov_b32 s59, -2
	v_add_u32_e32 v248, 0x10000, v143
	ds_read_b128 v[146:149], v248
	ds_read_b128 v[150:153], v248 offset:1024
	ds_read_b128 v[154:157], v248 offset:2048
	ds_read_b128 v[158:161], v248 offset:3072
	s_add_u32 s36, s30, 0xfff80080
	s_addc_u32 s37, s31, -1
	s_add_i32 s60, 0, 0x10000
	s_cmp_eq_u32 s59, 28
	s_cselect_b32 s41, s13, s37
	s_cselect_b32 s40, s55, s36
	s_cselect_b32 s37, s3, s58
	s_cselect_b32 s36, s56, s57
	s_add_i32 m0, s27, 0xc000
	ds_read_b128 v[180:183], v145
	ds_read_b128 v[184:187], v145 offset:1024
	ds_read_b128 v[188:191], v145 offset:2048
	ds_read_b128 v[192:195], v145 offset:3072
	ds_read_b128 v[196:199], v145 offset:4096
	ds_read_b128 v[200:203], v145 offset:5120
	ds_read_b128 v[208:211], v145 offset:6144
	ds_read_b128 v[212:215], v145 offset:7168
	global_load_lds_dwordx4 v138, s[30:31]
	s_add_i32 m0, s27, 0xe000
	s_nop 0
	global_load_lds_dwordx4 v140, s[30:31]
	s_waitcnt lgkmcnt(8)
	s_barrier
	s_waitcnt lgkmcnt(0)
	s_setprio 1
	s_waitcnt lgkmcnt(0)
	v_mfma_f32_16x16x32_bf16 v[128:131], v[146:149], v[180:183], 0
	v_mfma_f32_16x16x32_bf16 v[120:123], v[154:157], v[180:183], 0
	v_mfma_f32_16x16x32_bf16 v[112:115], v[146:149], v[188:191], 0
	v_mfma_f32_16x16x32_bf16 v[104:107], v[154:157], v[188:191], 0
	v_mfma_f32_16x16x32_bf16 v[96:99], v[146:149], v[196:199], 0
	v_mfma_f32_16x16x32_bf16 v[88:91], v[154:157], v[196:199], 0
	v_mfma_f32_16x16x32_bf16 v[80:83], v[146:149], v[208:211], 0
	v_mfma_f32_16x16x32_bf16 v[72:75], v[154:157], v[208:211], 0
	v_mfma_f32_16x16x32_bf16 v[128:131], v[150:153], v[184:187], v[128:131]
	v_mfma_f32_16x16x32_bf16 v[120:123], v[158:161], v[184:187], v[120:123]
	v_mfma_f32_16x16x32_bf16 v[112:115], v[150:153], v[192:195], v[112:115]
	v_mfma_f32_16x16x32_bf16 v[104:107], v[158:161], v[192:195], v[104:107]
	v_mfma_f32_16x16x32_bf16 v[96:99], v[150:153], v[200:203], v[96:99]
	v_mfma_f32_16x16x32_bf16 v[88:91], v[158:161], v[200:203], v[88:91]
	s_setprio 2
	s_barrier
	v_mfma_f32_16x16x32_bf16 v[80:83], v[150:153], v[212:215], v[80:83]
	v_mfma_f32_16x16x32_bf16 v[72:75], v[158:161], v[212:215], v[72:75]
	s_setprio 0
	s_add_i32 s62, 0, 0x14000
	s_add_i32 s60, s60, s47
	ds_read_b128 v[216:219], v248 offset:16384
	ds_read_b128 v[220:223], v248 offset:17408
	ds_read_b128 v[224:227], v248 offset:18432
	ds_read_b128 v[228:231], v248 offset:19456
	v_lshl_add_u64 v[162:163], s[36:37], 0, v[2:3]
	s_mov_b32 m0, s60
	v_lshl_add_u64 v[232:233], s[36:37], 0, v[132:133]
	global_load_lds_dwordx4 v[162:163], off
	s_add_i32 m0, s60, 0x2000
	s_nop 0
	global_load_lds_dwordx4 v[232:233], off
	s_barrier
	s_waitcnt lgkmcnt(0)
	s_setprio 1
	s_waitcnt lgkmcnt(0)
	v_mfma_f32_16x16x32_bf16 v[124:127], v[216:219], v[180:183], 0
	v_mfma_f32_16x16x32_bf16 v[116:119], v[224:227], v[180:183], 0
	v_mfma_f32_16x16x32_bf16 v[108:111], v[216:219], v[188:191], 0
	v_mfma_f32_16x16x32_bf16 v[100:103], v[224:227], v[188:191], 0
	v_mfma_f32_16x16x32_bf16 v[92:95], v[216:219], v[196:199], 0
	v_mfma_f32_16x16x32_bf16 v[84:87], v[224:227], v[196:199], 0
	v_mfma_f32_16x16x32_bf16 v[76:79], v[216:219], v[208:211], 0
	v_mfma_f32_16x16x32_bf16 v[68:71], v[224:227], v[208:211], 0
	v_mfma_f32_16x16x32_bf16 v[124:127], v[220:223], v[184:187], v[124:127]
	v_mfma_f32_16x16x32_bf16 v[116:119], v[228:231], v[184:187], v[116:119]
	v_mfma_f32_16x16x32_bf16 v[108:111], v[220:223], v[192:195], v[108:111]
	v_mfma_f32_16x16x32_bf16 v[100:103], v[228:231], v[192:195], v[100:103]
	v_mfma_f32_16x16x32_bf16 v[92:95], v[220:223], v[200:203], v[92:95]
	v_mfma_f32_16x16x32_bf16 v[84:87], v[228:231], v[200:203], v[84:87]
	s_setprio 2
	s_barrier
	v_mfma_f32_16x16x32_bf16 v[76:79], v[220:223], v[212:215], v[76:79]
	v_mfma_f32_16x16x32_bf16 v[68:71], v[228:231], v[212:215], v[68:71]
	s_setprio 0
	s_mov_b32 m0, s27
	v_lshl_add_u64 v[234:235], s[40:41], 0, v[136:137]
	ds_read_b128 v[180:183], v145 offset:16384
	ds_read_b128 v[184:187], v145 offset:17408
	ds_read_b128 v[188:191], v145 offset:18432
	ds_read_b128 v[192:195], v145 offset:19456
	ds_read_b128 v[196:199], v145 offset:20480
	ds_read_b128 v[200:203], v145 offset:21504
	ds_read_b128 v[208:211], v145 offset:22528
	ds_read_b128 v[212:215], v145 offset:23552
	global_load_lds_dwordx4 v[234:235], off
	v_lshl_add_u64 v[236:237], s[40:41], 0, v[134:135]
	s_mov_b32 m0, s48
	s_nop 0
	global_load_lds_dwordx4 v[236:237], off
	s_waitcnt vmcnt(10)
	s_barrier
	s_waitcnt lgkmcnt(0)
	s_setprio 1
	s_waitcnt lgkmcnt(0)
	v_mfma_f32_16x16x32_bf16 v[64:67], v[146:149], v[180:183], 0
	v_mfma_f32_16x16x32_bf16 v[56:59], v[154:157], v[180:183], 0
	v_mfma_f32_16x16x32_bf16 v[48:51], v[146:149], v[188:191], 0
	v_mfma_f32_16x16x32_bf16 v[40:43], v[154:157], v[188:191], 0
	v_mfma_f32_16x16x32_bf16 v[32:35], v[146:149], v[196:199], 0
	v_mfma_f32_16x16x32_bf16 v[24:27], v[154:157], v[196:199], 0
	v_mfma_f32_16x16x32_bf16 v[16:19], v[146:149], v[208:211], 0
	v_mfma_f32_16x16x32_bf16 v[8:11], v[154:157], v[208:211], 0
	v_mfma_f32_16x16x32_bf16 v[64:67], v[150:153], v[184:187], v[64:67]
	v_mfma_f32_16x16x32_bf16 v[56:59], v[158:161], v[184:187], v[56:59]
	v_mfma_f32_16x16x32_bf16 v[48:51], v[150:153], v[192:195], v[48:51]
	v_mfma_f32_16x16x32_bf16 v[40:43], v[158:161], v[192:195], v[40:43]
	v_mfma_f32_16x16x32_bf16 v[32:35], v[150:153], v[200:203], v[32:35]
	v_mfma_f32_16x16x32_bf16 v[24:27], v[158:161], v[200:203], v[24:27]
	s_setprio 2
	s_barrier
; #define PG8_STAGE(bufoff, gbase, voff) do { _Pragma("unroll") for (int _i = 0; _i < 2; ++_i) \
;     __builtin_amdgcn_global_load_lds((const unsigned*)((const char*)(gbase) + (voff)[_i]), (LAS unsigned*)(lds + (bufoff) + ldsw + _i * 8192), 16, 0, 0); } while (0)
; #define PG8_LDA(dst, b, h) do { _Pragma("unroll") for (int m = 0; m < 4; ++m) _Pragma("unroll") for (int k = 0; k < 2; ++k) dst[m][k] = *(const LAS bf16x8*)(lds + PG8_SA(b, h) + aoff + m * 2048 + k * 1024); } while (0)
; #define PG8_LDB(dst, b, h) do { _Pragma("unroll") for (int n = 0; n < 2; ++n) _Pragma("unroll") for (int k = 0; k < 2; ++k) dst[n][k] = *(const LAS bf16x8*)(lds + PG8_SB(b, h) + boff + n * 2048 + k * 1024); } while (0)
; #define PG8_MMA(ai, bj, At, Bt) do { __builtin_amdgcn_s_setprio(1); _Pragma("unroll") for (int m = 0; m < 4; ++m) _Pragma("unroll") for (int n = 0; n < 2; ++n) _Pragma("unroll") for (int k = 0; k < 2; ++k) \
;     acc[ai][bj][m][n] = __builtin_amdgcn_mfma_f32_16x16x32_bf16(Bt[n][k], At[m][k], acc[ai][bj][m][n], 0, 0, 0); __builtin_amdgcn_s_setprio(0); } while (0)
; #define PG8_WAIT_V(n) asm volatile("s_waitcnt vmcnt(" #n ")" ::: "memory")
; #define PG8_WAIT_L(n) asm volatile("s_waitcnt lgkmcnt(" #n ")" ::: "memory")
; #define PG8_BAR __builtin_amdgcn_s_barrier()
; #define PG8_SCHED __builtin_amdgcn_sched_barrier(0)
; template <class Epi>
; DI void gemm_phase(LAS unsigned char* lds, const Gemm g, const Epi& E) {
;     ...
;       PG8_BAR; PG8_WAIT_L(0); PG8_MMA(1, 0, At, B0); PG8_BAR; PG8_SCHED;
;       PG8_STAGE(PG8_SB(0, 1), b2 + hstepB, voffB);
;       PG8_WAIT_V(6); PG8_BAR; PG8_MMA(1, 1, At, B1); PG8_BAR;
;       PG8_LDB(B0, 1, 0); PG8_SCHED; PG8_LDA(At, 1, 0); PG8_STAGE(PG8_SA(0, 1), a2 + hstepA, voffA);
;       PG8_WAIT_L(8); PG8_BAR; PG8_WAIT_L(0); PG8_MMA(0, 0, At, B0); PG8_BAR; PG8_SCHED;
;       PG8_LDB(B1, 1, 1); PG8_STAGE(PG8_SB(1, 0), b3, voffB);
;       PG8_BAR; PG8_WAIT_L(0); PG8_MMA(0, 1, At, B1); PG8_BAR;
	v_mfma_f32_16x16x32_bf16 v[16:19], v[150:153], v[212:215], v[16:19]
	v_mfma_f32_16x16x32_bf16 v[8:11], v[158:161], v[212:215], v[8:11]
	s_setprio 0
	ds_read_b128 v[146:149], v248 offset:32768
	ds_read_b128 v[150:153], v248 offset:33792
	ds_read_b128 v[154:157], v248 offset:34816
	ds_read_b128 v[158:161], v248 offset:35840
	s_add_u32 s60, s36, 0x80000
	s_addc_u32 s61, s37, 0
	s_add_i32 s62, s62, s47
	s_mov_b32 m0, s62
	s_nop 0
	global_load_lds_dwordx4 v2, s[60:61]
	s_add_i32 m0, s62, 0x2000
	s_nop 0
	global_load_lds_dwordx4 v132, s[60:61]
	s_waitcnt vmcnt(6)
	s_barrier
	s_setprio 1
	v_mfma_f32_16x16x32_bf16 v[60:63], v[216:219], v[180:183], 0
	v_mfma_f32_16x16x32_bf16 v[52:55], v[224:227], v[180:183], 0
	v_mfma_f32_16x16x32_bf16 v[44:47], v[216:219], v[188:191], 0
	v_mfma_f32_16x16x32_bf16 v[36:39], v[224:227], v[188:191], 0
	v_mfma_f32_16x16x32_bf16 v[28:31], v[216:219], v[196:199], 0
	v_mfma_f32_16x16x32_bf16 v[20:23], v[224:227], v[196:199], 0
	v_mfma_f32_16x16x32_bf16 v[12:15], v[216:219], v[208:211], 0
	v_mfma_f32_16x16x32_bf16 v[4:7], v[224:227], v[208:211], 0
	v_mfma_f32_16x16x32_bf16 v[60:63], v[220:223], v[184:187], v[60:63]
	v_mfma_f32_16x16x32_bf16 v[52:55], v[228:231], v[184:187], v[52:55]
	v_mfma_f32_16x16x32_bf16 v[44:47], v[220:223], v[192:195], v[44:47]
	v_mfma_f32_16x16x32_bf16 v[36:39], v[228:231], v[192:195], v[36:39]
	v_mfma_f32_16x16x32_bf16 v[28:31], v[220:223], v[200:203], v[28:31]
	v_mfma_f32_16x16x32_bf16 v[20:23], v[228:231], v[200:203], v[20:23]
	s_setprio 2
	s_barrier
	v_mfma_f32_16x16x32_bf16 v[12:15], v[220:223], v[212:215], v[12:15]
	v_mfma_f32_16x16x32_bf16 v[4:7], v[228:231], v[212:215], v[4:7]
	s_setprio 0
	s_add_i32 s60, 0, 0x18000
	s_add_u32 s40, s40, 0x80000
	s_addc_u32 s41, s41, 0
	s_mov_b32 m0, s49
	ds_read_b128 v[180:183], v145 offset:32768
	ds_read_b128 v[184:187], v145 offset:33792
	ds_read_b128 v[188:191], v145 offset:34816
	ds_read_b128 v[192:195], v145 offset:35840
	ds_read_b128 v[196:199], v145 offset:36864
	ds_read_b128 v[200:203], v145 offset:37888
	ds_read_b128 v[208:211], v145 offset:38912
	ds_read_b128 v[212:215], v145 offset:39936
	global_load_lds_dwordx4 v136, s[40:41]
	s_mov_b32 m0, s50
	s_nop 0
	global_load_lds_dwordx4 v134, s[40:41]
	s_waitcnt lgkmcnt(8)
	s_barrier
	s_waitcnt lgkmcnt(0)
	s_setprio 1
	s_waitcnt lgkmcnt(0)
	v_mfma_f32_16x16x32_bf16 v[128:131], v[146:149], v[180:183], v[128:131]
	v_mfma_f32_16x16x32_bf16 v[120:123], v[154:157], v[180:183], v[120:123]
	v_mfma_f32_16x16x32_bf16 v[112:115], v[146:149], v[188:191], v[112:115]
	v_mfma_f32_16x16x32_bf16 v[104:107], v[154:157], v[188:191], v[104:107]
	v_mfma_f32_16x16x32_bf16 v[96:99], v[146:149], v[196:199], v[96:99]
	v_mfma_f32_16x16x32_bf16 v[88:91], v[154:157], v[196:199], v[88:91]
	v_mfma_f32_16x16x32_bf16 v[80:83], v[146:149], v[208:211], v[80:83]
	v_mfma_f32_16x16x32_bf16 v[72:75], v[154:157], v[208:211], v[72:75]
	v_mfma_f32_16x16x32_bf16 v[128:131], v[150:153], v[184:187], v[128:131]
	v_mfma_f32_16x16x32_bf16 v[120:123], v[158:161], v[184:187], v[120:123]
	v_mfma_f32_16x16x32_bf16 v[112:115], v[150:153], v[192:195], v[112:115]
	v_mfma_f32_16x16x32_bf16 v[104:107], v[158:161], v[192:195], v[104:107]
	v_mfma_f32_16x16x32_bf16 v[96:99], v[150:153], v[200:203], v[96:99]
	v_mfma_f32_16x16x32_bf16 v[88:91], v[158:161], v[200:203], v[88:91]
	s_setprio 2
	s_barrier
	v_mfma_f32_16x16x32_bf16 v[80:83], v[150:153], v[212:215], v[80:83]
	v_mfma_f32_16x16x32_bf16 v[72:75], v[158:161], v[212:215], v[72:75]
	s_setprio 0
	s_add_i32 s40, 0, 0x1c000
	s_add_i32 s41, s60, s47
	v_lshl_add_u64 v[162:163], v[162:163], 0, s[84:85]
	s_mov_b32 m0, s41
	ds_read_b128 v[216:219], v248 offset:49152
	ds_read_b128 v[220:223], v248 offset:50176
	ds_read_b128 v[224:227], v248 offset:51200
	ds_read_b128 v[228:231], v248 offset:52224
	global_load_lds_dwordx4 v[162:163], off
	v_lshl_add_u64 v[162:163], v[232:233], 0, s[84:85]
	s_add_i32 m0, s41, 0x2000
	s_nop 0
	global_load_lds_dwordx4 v[162:163], off
	s_barrier
; #define PG8_STAGE(bufoff, gbase, voff) do { _Pragma("unroll") for (int _i = 0; _i < 2; ++_i) \
;     __builtin_amdgcn_global_load_lds((const unsigned*)((const char*)(gbase) + (voff)[_i]), (LAS unsigned*)(lds + (bufoff) + ldsw + _i * 8192), 16, 0, 0); } while (0)
; #define PG8_LDA(dst, b, h) do { _Pragma("unroll") for (int m = 0; m < 4; ++m) _Pragma("unroll") for (int k = 0; k < 2; ++k) dst[m][k] = *(const LAS bf16x8*)(lds + PG8_SA(b, h) + aoff + m * 2048 + k * 1024); } while (0)
; #define PG8_MMA(ai, bj, At, Bt) do { __builtin_amdgcn_s_setprio(1); _Pragma("unroll") for (int m = 0; m < 4; ++m) _Pragma("unroll") for (int n = 0; n < 2; ++n) _Pragma("unroll") for (int k = 0; k < 2; ++k) \
;     acc[ai][bj][m][n] = __builtin_amdgcn_mfma_f32_16x16x32_bf16(Bt[n][k], At[m][k], acc[ai][bj][m][n], 0, 0, 0); __builtin_amdgcn_s_setprio(0); } while (0)
; #define PG8_WAIT_V(n) asm volatile("s_waitcnt vmcnt(" #n ")" ::: "memory")
; #define PG8_WAIT_L(n) asm volatile("s_waitcnt lgkmcnt(" #n ")" ::: "memory")
; #define PG8_BAR __builtin_amdgcn_s_barrier()
; #define PG8_SCHED __builtin_amdgcn_sched_barrier(0)
; template <class Epi>
; DI void gemm_phase(LAS unsigned char* lds, const Gemm g, const Epi& E) {
;     ...
;       PG8_BAR; PG8_WAIT_L(0); PG8_MMA(0, 1, At, B1); PG8_BAR;
;       PG8_LDA(At, 1, 1); PG8_STAGE(PG8_SA(1, 0), a3, voffA);
;       PG8_BAR; PG8_WAIT_L(0); PG8_MMA(1, 0, At, B0); PG8_BAR; PG8_SCHED;
;       PG8_STAGE(PG8_SB(1, 1), b3 + hstepB, voffB);
;       PG8_WAIT_V(6); PG8_BAR; PG8_MMA(1, 1, At, B1); PG8_BAR;
	s_waitcnt lgkmcnt(0)
	s_setprio 1
	s_waitcnt lgkmcnt(0)
	v_mfma_f32_16x16x32_bf16 v[124:127], v[216:219], v[180:183], v[124:127]
	v_mfma_f32_16x16x32_bf16 v[116:119], v[224:227], v[180:183], v[116:119]
	v_mfma_f32_16x16x32_bf16 v[108:111], v[216:219], v[188:191], v[108:111]
	v_mfma_f32_16x16x32_bf16 v[100:103], v[224:227], v[188:191], v[100:103]
	v_mfma_f32_16x16x32_bf16 v[92:95], v[216:219], v[196:199], v[92:95]
	v_mfma_f32_16x16x32_bf16 v[84:87], v[224:227], v[196:199], v[84:87]
	v_mfma_f32_16x16x32_bf16 v[76:79], v[216:219], v[208:211], v[76:79]
	v_mfma_f32_16x16x32_bf16 v[68:71], v[224:227], v[208:211], v[68:71]
	v_mfma_f32_16x16x32_bf16 v[124:127], v[220:223], v[184:187], v[124:127]
	v_mfma_f32_16x16x32_bf16 v[116:119], v[228:231], v[184:187], v[116:119]
	v_mfma_f32_16x16x32_bf16 v[108:111], v[220:223], v[192:195], v[108:111]
	v_mfma_f32_16x16x32_bf16 v[100:103], v[228:231], v[192:195], v[100:103]
	v_mfma_f32_16x16x32_bf16 v[92:95], v[220:223], v[200:203], v[92:95]
	v_mfma_f32_16x16x32_bf16 v[84:87], v[228:231], v[200:203], v[84:87]
	s_setprio 2
	s_barrier
	v_mfma_f32_16x16x32_bf16 v[76:79], v[220:223], v[212:215], v[76:79]
	v_mfma_f32_16x16x32_bf16 v[68:71], v[228:231], v[212:215], v[68:71]
	s_setprio 0
	s_mov_b32 m0, s51
	v_lshl_add_u64 v[162:163], v[234:235], 0, s[84:85]
	ds_read_b128 v[180:183], v145 offset:49152
	ds_read_b128 v[184:187], v145 offset:50176
	ds_read_b128 v[188:191], v145 offset:51200
	ds_read_b128 v[192:195], v145 offset:52224
	ds_read_b128 v[196:199], v145 offset:53248
	ds_read_b128 v[200:203], v145 offset:54272
	ds_read_b128 v[208:211], v145 offset:55296
	ds_read_b128 v[212:215], v145 offset:56320
	global_load_lds_dwordx4 v[162:163], off
	v_lshl_add_u64 v[162:163], v[236:237], 0, s[84:85]
	s_mov_b32 m0, s52
	s_nop 0
	global_load_lds_dwordx4 v[162:163], off
	s_waitcnt vmcnt(10)
	s_barrier
	s_waitcnt lgkmcnt(0)
	s_setprio 1
	s_waitcnt lgkmcnt(0)
	v_mfma_f32_16x16x32_bf16 v[64:67], v[146:149], v[180:183], v[64:67]
	v_mfma_f32_16x16x32_bf16 v[56:59], v[154:157], v[180:183], v[56:59]
	v_mfma_f32_16x16x32_bf16 v[48:51], v[146:149], v[188:191], v[48:51]
	v_mfma_f32_16x16x32_bf16 v[40:43], v[154:157], v[188:191], v[40:43]
	v_mfma_f32_16x16x32_bf16 v[32:35], v[146:149], v[196:199], v[32:35]
	v_mfma_f32_16x16x32_bf16 v[24:27], v[154:157], v[196:199], v[24:27]
	v_mfma_f32_16x16x32_bf16 v[16:19], v[146:149], v[208:211], v[16:19]
	v_mfma_f32_16x16x32_bf16 v[8:11], v[154:157], v[208:211], v[8:11]
	v_mfma_f32_16x16x32_bf16 v[64:67], v[150:153], v[184:187], v[64:67]
	v_mfma_f32_16x16x32_bf16 v[56:59], v[158:161], v[184:187], v[56:59]
	v_mfma_f32_16x16x32_bf16 v[48:51], v[150:153], v[192:195], v[48:51]
	v_mfma_f32_16x16x32_bf16 v[40:43], v[158:161], v[192:195], v[40:43]
	v_mfma_f32_16x16x32_bf16 v[32:35], v[150:153], v[200:203], v[32:35]
	v_mfma_f32_16x16x32_bf16 v[24:27], v[158:161], v[200:203], v[24:27]
	s_setprio 2
	s_barrier
	v_mfma_f32_16x16x32_bf16 v[16:19], v[150:153], v[212:215], v[16:19]
	v_mfma_f32_16x16x32_bf16 v[8:11], v[158:161], v[212:215], v[8:11]
	s_setprio 0
	ds_read_b128 v[146:149], v248
	ds_read_b128 v[150:153], v248 offset:1024
	ds_read_b128 v[154:157], v248 offset:2048
	ds_read_b128 v[158:161], v248 offset:3072
	s_add_u32 s36, s36, 0x80080
	s_addc_u32 s37, s37, 0
	s_add_i32 s40, s40, s47
	s_mov_b32 m0, s40
	s_nop 0
	global_load_lds_dwordx4 v2, s[36:37]
	s_add_i32 m0, s40, 0x2000
	s_nop 0
	global_load_lds_dwordx4 v132, s[36:37]
	s_waitcnt vmcnt(6)
	s_barrier
	s_setprio 1
	v_mfma_f32_16x16x32_bf16 v[60:63], v[216:219], v[180:183], v[60:63]
	v_mfma_f32_16x16x32_bf16 v[52:55], v[224:227], v[180:183], v[52:55]
	v_mfma_f32_16x16x32_bf16 v[44:47], v[216:219], v[188:191], v[44:47]
	v_mfma_f32_16x16x32_bf16 v[36:39], v[224:227], v[188:191], v[36:39]
	v_mfma_f32_16x16x32_bf16 v[28:31], v[216:219], v[196:199], v[28:31]
	v_mfma_f32_16x16x32_bf16 v[20:23], v[224:227], v[196:199], v[20:23]
	v_mfma_f32_16x16x32_bf16 v[12:15], v[216:219], v[208:211], v[12:15]
	v_mfma_f32_16x16x32_bf16 v[4:7], v[224:227], v[208:211], v[4:7]
	v_mfma_f32_16x16x32_bf16 v[60:63], v[220:223], v[184:187], v[60:63]
	v_mfma_f32_16x16x32_bf16 v[52:55], v[228:231], v[184:187], v[52:55]
	v_mfma_f32_16x16x32_bf16 v[44:47], v[220:223], v[192:195], v[44:47]
	v_mfma_f32_16x16x32_bf16 v[36:39], v[228:231], v[192:195], v[36:39]
	v_mfma_f32_16x16x32_bf16 v[28:31], v[220:223], v[200:203], v[28:31]
	v_mfma_f32_16x16x32_bf16 v[20:23], v[228:231], v[200:203], v[20:23]
	s_setprio 2
	s_barrier
	v_mfma_f32_16x16x32_bf16 v[12:15], v[220:223], v[212:215], v[12:15]
	v_mfma_f32_16x16x32_bf16 v[4:7], v[228:231], v[212:215], v[4:7]
	s_setprio 0
	s_add_i32 s59, s59, 2
	s_add_u32 s30, s30, 0x100
	s_addc_u32 s31, s31, 0
	s_add_u32 s57, s57, 0x100
	s_addc_u32 s58, s58, 0
	s_cmp_gt_u32 s59, 29
	s_cbranch_scc1 .Lpeel_exit_190

; DI unsigned cvt_pk_bf16(float lo, float hi) { const f32x2 v = {lo, hi}; const bf16x2_t r = __builtin_convertvector(v, bf16x2_t); return __builtin_bit_cast(unsigned, r); }
; DI float silu_f(float g) { return g * __builtin_amdgcn_rcpf(1.0f + __expf(-g)); }
;   DI void operator()(const f32x4 (&acc)[2][2][4][2], const Unit& u, int wr, int wc, int fr, int fq) const {
;     const int row0 = u.pm * BM + wr * 64 + fr, col0 = u.pn * HALF + wc * 32 + 8 * fq;
; #pragma unroll
;     for (int ai = 0; ai < 2; ++ai)
; #pragma unroll
;       for (int m = 0; m < 4; ++m) {
;         const f32x4 g0 = acc[ai][0][m][0], g1 = acc[ai][0][m][1], u0 = acc[ai][1][m][0], u1 = acc[ai][1][m][1];
;         u32x4 w;
;         w.x = cvt_pk_bf16(silu_f(g0[0]) * u0[0], silu_f(g0[1]) * u0[1]); w.y = cvt_pk_bf16(silu_f(g0[2]) * u0[2], silu_f(g0[3]) * u0[3]);
;         w.z = cvt_pk_bf16(silu_f(g1[0]) * u1[0], silu_f(g1[1]) * u1[1]); w.w = cvt_pk_bf16(silu_f(g1[2]) * u1[2], silu_f(g1[3]) * u1[3]);
;         *(u32x4*)(H + (size_t)(row0 + ai * HALF + m * 16) * DFF + col0) = w;
.Lpeel_exit_190:
	s_waitcnt lgkmcnt(0)
	v_mul_f32_e32 v147, 0xbfb8aa3b, v128
	v_exp_f32_e32 v147, v147
	v_lshl_or_b32 v148, s54, 7, v144
	v_lshl_add_u32 v146, s26, 8, v142
	v_ashrrev_i32_e32 v149, 31, v148
	v_add_f32_e32 v147, 1.0, v147
	v_rcp_f32_e32 v150, v147
	v_mul_f32_e32 v147, 0xbfb8aa3b, v129
	v_exp_f32_e32 v147, v147
	s_movk_i32 s3, 0x2c00
	s_movk_i32 s5, 0x2c00
	s_and_b64 vcc, exec, s[38:39]
	v_add_f32_e32 v147, 1.0, v147
	v_rcp_f32_e32 v151, v147
	s_mov_b32 s54, s2
	s_mov_b32 s26, s12
	s_mov_b64 s[36:37], s[22:23]
	v_pk_mul_f32 v[128:129], v[128:129], v[150:151]
	s_nop 0
	v_pk_mul_f32 v[124:125], v[128:129], v[124:125]
	s_nop 0
	v_cvt_pk_bf16_f32 v124, v124, v125
	v_mul_f32_e32 v125, 0xbfb8aa3b, v130
	v_exp_f32_e32 v125, v125
	s_nop 0
	v_add_f32_e32 v125, 1.0, v125
	v_rcp_f32_e32 v128, v125
	v_mul_f32_e32 v125, 0xbfb8aa3b, v131
	v_exp_f32_e32 v125, v125
	s_nop 0
	v_add_f32_e32 v125, 1.0, v125
	v_rcp_f32_e32 v129, v125
	s_nop 0
	v_pk_mul_f32 v[128:129], v[130:131], v[128:129]
	s_nop 0
	v_pk_mul_f32 v[126:127], v[128:129], v[126:127]
	s_nop 0
	v_cvt_pk_bf16_f32 v125, v126, v127
	v_mul_f32_e32 v126, 0xbfb8aa3b, v120
	v_mul_f32_e32 v127, 0xbfb8aa3b, v121
	v_exp_f32_e32 v126, v126
	v_exp_f32_e32 v127, v127
	v_add_f32_e32 v126, 1.0, v126
	v_add_f32_e32 v127, 1.0, v127
	v_rcp_f32_e32 v126, v126
	v_rcp_f32_e32 v127, v127
	s_nop 0
	v_pk_mul_f32 v[120:121], v[120:121], v[126:127]
	s_nop 0
	v_pk_mul_f32 v[116:117], v[120:121], v[116:117]
	s_nop 0
	v_cvt_pk_bf16_f32 v126, v116, v117
	v_mul_f32_e32 v116, 0xbfb8aa3b, v122
	v_mul_f32_e32 v117, 0xbfb8aa3b, v123
	v_exp_f32_e32 v116, v116
	v_exp_f32_e32 v117, v117
	v_add_f32_e32 v116, 1.0, v116
	v_add_f32_e32 v117, 1.0, v117
	v_rcp_f32_e32 v116, v116
	v_rcp_f32_e32 v117, v117
	s_nop 0
	v_pk_mul_f32 v[116:117], v[122:123], v[116:117]
	s_nop 0
	v_pk_mul_f32 v[116:117], v[116:117], v[118:119]
	v_lshlrev_b64 v[118:119], 1, v[148:149]
	v_cvt_pk_bf16_f32 v127, v116, v117
	v_mov_b64_e32 v[116:117], s[0:1]
	v_mad_i64_i32 v[120:121], s[30:31], v146, s3, v[116:117]
	v_lshl_add_u64 v[120:121], v[120:121], 0, v[118:119]
	global_store_dwordx4 v[120:121], v[124:127], off
	v_mul_f32_e32 v120, 0xbfb8aa3b, v112
	v_mul_f32_e32 v121, 0xbfb8aa3b, v113
	v_exp_f32_e32 v120, v120
	v_exp_f32_e32 v121, v121
	v_add_f32_e32 v120, 1.0, v120
	v_add_f32_e32 v121, 1.0, v121
	v_rcp_f32_e32 v120, v120
	v_rcp_f32_e32 v121, v121
	s_nop 0
	v_pk_mul_f32 v[112:113], v[112:113], v[120:121]
	s_nop 0
	v_pk_mul_f32 v[108:109], v[112:113], v[108:109]
	s_nop 0
	v_cvt_pk_bf16_f32 v108, v108, v109
	v_mul_f32_e32 v109, 0xbfb8aa3b, v114
	v_exp_f32_e32 v109, v109
	s_nop 0
	v_add_f32_e32 v109, 1.0, v109
	v_rcp_f32_e32 v112, v109
	v_mul_f32_e32 v109, 0xbfb8aa3b, v115
	v_exp_f32_e32 v109, v109
	s_nop 0
	v_add_f32_e32 v109, 1.0, v109
	v_rcp_f32_e32 v113, v109
	s_nop 0
	v_pk_mul_f32 v[112:113], v[114:115], v[112:113]
	s_nop 0
	v_pk_mul_f32 v[110:111], v[112:113], v[110:111]
	s_nop 0
	v_cvt_pk_bf16_f32 v109, v110, v111
	v_mul_f32_e32 v110, 0xbfb8aa3b, v104
	v_mul_f32_e32 v111, 0xbfb8aa3b, v105
	v_exp_f32_e32 v110, v110
	v_exp_f32_e32 v111, v111
	v_add_f32_e32 v110, 1.0, v110
	v_add_f32_e32 v111, 1.0, v111
	v_rcp_f32_e32 v110, v110
	v_rcp_f32_e32 v111, v111
	s_nop 0
	v_pk_mul_f32 v[104:105], v[104:105], v[110:111]
	s_nop 0
	v_pk_mul_f32 v[100:101], v[104:105], v[100:101]
	s_nop 0
	v_cvt_pk_bf16_f32 v110, v100, v101
	v_mul_f32_e32 v100, 0xbfb8aa3b, v106
	v_mul_f32_e32 v101, 0xbfb8aa3b, v107
	v_exp_f32_e32 v100, v100
	v_exp_f32_e32 v101, v101
	v_add_f32_e32 v100, 1.0, v100
	v_add_f32_e32 v101, 1.0, v101
	v_rcp_f32_e32 v100, v100
	v_rcp_f32_e32 v101, v101
	s_nop 0
	v_pk_mul_f32 v[100:101], v[106:107], v[100:101]
	s_nop 0
	v_pk_mul_f32 v[100:101], v[100:101], v[102:103]
	s_nop 0
	v_cvt_pk_bf16_f32 v111, v100, v101
	v_or_b32_e32 v100, 16, v146
	v_mad_i64_i32 v[100:101], s[30:31], v100, s3, v[116:117]
	v_lshl_add_u64 v[100:101], v[100:101], 0, v[118:119]
	global_store_dwordx4 v[100:101], v[108:111], off
	v_mul_f32_e32 v100, 0xbfb8aa3b, v96
	v_mul_f32_e32 v101, 0xbfb8aa3b, v97
	v_exp_f32_e32 v100, v100
	v_exp_f32_e32 v101, v101
	v_add_f32_e32 v100, 1.0, v100
	v_add_f32_e32 v101, 1.0, v101
	v_rcp_f32_e32 v100, v100
	v_rcp_f32_e32 v101, v101
	s_nop 0
	v_pk_mul_f32 v[96:97], v[96:97], v[100:101]
	s_nop 0
	v_pk_mul_f32 v[92:93], v[96:97], v[92:93]
	s_nop 0
	v_cvt_pk_bf16_f32 v92, v92, v93
	v_mul_f32_e32 v93, 0xbfb8aa3b, v98
	v_exp_f32_e32 v93, v93
	s_nop 0
	v_add_f32_e32 v93, 1.0, v93
	v_rcp_f32_e32 v96, v93
	v_mul_f32_e32 v93, 0xbfb8aa3b, v99
	v_exp_f32_e32 v93, v93
	s_nop 0
	v_add_f32_e32 v93, 1.0, v93
	v_rcp_f32_e32 v97, v93
	s_nop 0
	v_pk_mul_f32 v[96:97], v[98:99], v[96:97]
	s_nop 0
	v_pk_mul_f32 v[94:95], v[96:97], v[94:95]
	s_nop 0
	v_cvt_pk_bf16_f32 v93, v94, v95
	v_mul_f32_e32 v94, 0xbfb8aa3b, v88
	v_mul_f32_e32 v95, 0xbfb8aa3b, v89
	v_exp_f32_e32 v94, v94
	v_exp_f32_e32 v95, v95
	v_add_f32_e32 v94, 1.0, v94
	v_add_f32_e32 v95, 1.0, v95
	v_rcp_f32_e32 v94, v94
	v_rcp_f32_e32 v95, v95
	s_nop 0
	v_pk_mul_f32 v[88:89], v[88:89], v[94:95]
	s_nop 0
	v_pk_mul_f32 v[84:85], v[88:89], v[84:85]
	s_nop 0
	v_cvt_pk_bf16_f32 v94, v84, v85
	v_mul_f32_e32 v84, 0xbfb8aa3b, v90
	v_mul_f32_e32 v85, 0xbfb8aa3b, v91
	v_exp_f32_e32 v84, v84
	v_exp_f32_e32 v85, v85
	v_add_f32_e32 v84, 1.0, v84
	v_add_f32_e32 v85, 1.0, v85
	v_rcp_f32_e32 v84, v84
	v_rcp_f32_e32 v85, v85
	s_nop 0
	v_pk_mul_f32 v[84:85], v[90:91], v[84:85]
	s_nop 0
	v_pk_mul_f32 v[84:85], v[84:85], v[86:87]
	s_nop 0
	v_cvt_pk_bf16_f32 v95, v84, v85
	v_or_b32_e32 v84, 32, v146
	v_mad_i64_i32 v[84:85], s[30:31], v84, s3, v[116:117]
	v_lshl_add_u64 v[84:85], v[84:85], 0, v[118:119]
	global_store_dwordx4 v[84:85], v[92:95], off
; DI unsigned cvt_pk_bf16(float lo, float hi) { const f32x2 v = {lo, hi}; const bf16x2_t r = __builtin_convertvector(v, bf16x2_t); return __builtin_bit_cast(unsigned, r); }
; DI float silu_f(float g) { return g * __builtin_amdgcn_rcpf(1.0f + __expf(-g)); }
;   DI void operator()(const f32x4 (&acc)[2][2][4][2], const Unit& u, int wr, int wc, int fr, int fq) const {
;     const int row0 = u.pm * BM + wr * 64 + fr, col0 = u.pn * HALF + wc * 32 + 8 * fq;
; #pragma unroll
;     for (int ai = 0; ai < 2; ++ai)
; #pragma unroll
;       for (int m = 0; m < 4; ++m) {
;         const f32x4 g0 = acc[ai][0][m][0], g1 = acc[ai][0][m][1], u0 = acc[ai][1][m][0], u1 = acc[ai][1][m][1];
;         u32x4 w;
;         w.x = cvt_pk_bf16(silu_f(g0[0]) * u0[0], silu_f(g0[1]) * u0[1]); w.y = cvt_pk_bf16(silu_f(g0[2]) * u0[2], silu_f(g0[3]) * u0[3]);
;         w.z = cvt_pk_bf16(silu_f(g1[0]) * u1[0], silu_f(g1[1]) * u1[1]); w.w = cvt_pk_bf16(silu_f(g1[2]) * u1[2], silu_f(g1[3]) * u1[3]);
;         *(u32x4*)(H + (size_t)(row0 + ai * HALF + m * 16) * DFF + col0) = w;
	v_mul_f32_e32 v84, 0xbfb8aa3b, v80
	v_mul_f32_e32 v85, 0xbfb8aa3b, v81
	v_exp_f32_e32 v84, v84
	v_exp_f32_e32 v85, v85
	v_add_f32_e32 v84, 1.0, v84
	v_add_f32_e32 v85, 1.0, v85
	v_rcp_f32_e32 v84, v84
	v_rcp_f32_e32 v85, v85
	s_nop 0
	v_pk_mul_f32 v[80:81], v[80:81], v[84:85]
	s_nop 0
	v_pk_mul_f32 v[76:77], v[80:81], v[76:77]
	s_nop 0
	v_cvt_pk_bf16_f32 v76, v76, v77
	v_mul_f32_e32 v77, 0xbfb8aa3b, v82
	v_exp_f32_e32 v77, v77
	s_nop 0
	v_add_f32_e32 v77, 1.0, v77
	v_rcp_f32_e32 v80, v77
	v_mul_f32_e32 v77, 0xbfb8aa3b, v83
	v_exp_f32_e32 v77, v77
	s_nop 0
	v_add_f32_e32 v77, 1.0, v77
	v_rcp_f32_e32 v81, v77
	s_nop 0
	v_pk_mul_f32 v[80:81], v[82:83], v[80:81]
	s_nop 0
	v_pk_mul_f32 v[78:79], v[80:81], v[78:79]
	s_nop 0
	v_cvt_pk_bf16_f32 v77, v78, v79
	v_mul_f32_e32 v78, 0xbfb8aa3b, v72
	v_mul_f32_e32 v79, 0xbfb8aa3b, v73
	v_exp_f32_e32 v78, v78
	v_exp_f32_e32 v79, v79
	v_add_f32_e32 v78, 1.0, v78
	v_add_f32_e32 v79, 1.0, v79
	v_rcp_f32_e32 v78, v78
	v_rcp_f32_e32 v79, v79
	s_nop 0
	v_pk_mul_f32 v[72:73], v[72:73], v[78:79]
	s_nop 0
	v_pk_mul_f32 v[68:69], v[72:73], v[68:69]
	s_nop 0
	v_cvt_pk_bf16_f32 v78, v68, v69
	v_mul_f32_e32 v68, 0xbfb8aa3b, v74
	v_mul_f32_e32 v69, 0xbfb8aa3b, v75
	v_exp_f32_e32 v68, v68
	v_exp_f32_e32 v69, v69
	v_add_f32_e32 v68, 1.0, v68
	v_add_f32_e32 v69, 1.0, v69
	v_rcp_f32_e32 v68, v68
	v_rcp_f32_e32 v69, v69
	s_nop 0
	v_pk_mul_f32 v[68:69], v[74:75], v[68:69]
	s_nop 0
	v_pk_mul_f32 v[68:69], v[68:69], v[70:71]
	v_add_u32_e32 v70, 0x80, v146
	v_cvt_pk_bf16_f32 v79, v68, v69
	v_or_b32_e32 v68, 48, v146
	v_mad_i64_i32 v[68:69], s[30:31], v68, s3, v[116:117]
	v_lshl_add_u64 v[68:69], v[68:69], 0, v[118:119]
	global_store_dwordx4 v[68:69], v[76:79], off
	v_mul_f32_e32 v68, 0xbfb8aa3b, v64
	v_mul_f32_e32 v69, 0xbfb8aa3b, v65
	v_exp_f32_e32 v68, v68
	v_exp_f32_e32 v69, v69
	v_add_f32_e32 v68, 1.0, v68
	v_add_f32_e32 v69, 1.0, v69
	v_rcp_f32_e32 v68, v68
	v_rcp_f32_e32 v69, v69
	s_nop 0
	v_pk_mul_f32 v[64:65], v[64:65], v[68:69]
	s_nop 0
	v_pk_mul_f32 v[60:61], v[64:65], v[60:61]
	s_nop 0
	v_cvt_pk_bf16_f32 v60, v60, v61
	v_mul_f32_e32 v61, 0xbfb8aa3b, v66
	v_exp_f32_e32 v61, v61
	s_nop 0
	v_add_f32_e32 v61, 1.0, v61
	v_rcp_f32_e32 v64, v61
	v_mul_f32_e32 v61, 0xbfb8aa3b, v67
	v_exp_f32_e32 v61, v61
	s_nop 0
	v_add_f32_e32 v61, 1.0, v61
	v_rcp_f32_e32 v65, v61
	s_nop 0
	v_pk_mul_f32 v[64:65], v[66:67], v[64:65]
	s_nop 0
	v_pk_mul_f32 v[62:63], v[64:65], v[62:63]
	s_nop 0
	v_cvt_pk_bf16_f32 v61, v62, v63
	v_mul_f32_e32 v62, 0xbfb8aa3b, v56
	v_mul_f32_e32 v63, 0xbfb8aa3b, v57
	v_exp_f32_e32 v62, v62
	v_exp_f32_e32 v63, v63
	v_add_f32_e32 v62, 1.0, v62
	v_add_f32_e32 v63, 1.0, v63
	v_rcp_f32_e32 v62, v62
	v_rcp_f32_e32 v63, v63
	s_nop 0
	v_pk_mul_f32 v[56:57], v[56:57], v[62:63]
	s_nop 0
	v_pk_mul_f32 v[52:53], v[56:57], v[52:53]
	s_nop 0
	v_cvt_pk_bf16_f32 v62, v52, v53
	v_mul_f32_e32 v52, 0xbfb8aa3b, v58
	v_mul_f32_e32 v53, 0xbfb8aa3b, v59
	v_exp_f32_e32 v52, v52
	v_exp_f32_e32 v53, v53
	v_add_f32_e32 v52, 1.0, v52
	v_add_f32_e32 v53, 1.0, v53
	v_rcp_f32_e32 v52, v52
	v_rcp_f32_e32 v53, v53
	s_nop 0
	v_pk_mul_f32 v[52:53], v[58:59], v[52:53]
	s_nop 0
	v_pk_mul_f32 v[52:53], v[52:53], v[54:55]
	s_nop 0
	v_cvt_pk_bf16_f32 v63, v52, v53
	v_mad_i64_i32 v[52:53], s[30:31], v70, s3, v[116:117]
	v_lshl_add_u64 v[52:53], v[52:53], 0, v[118:119]
	global_store_dwordx4 v[52:53], v[60:63], off
	v_mul_f32_e32 v52, 0xbfb8aa3b, v48
	v_mul_f32_e32 v53, 0xbfb8aa3b, v49
	v_exp_f32_e32 v52, v52
	v_exp_f32_e32 v53, v53
	v_add_f32_e32 v52, 1.0, v52
	v_add_f32_e32 v53, 1.0, v53
	v_rcp_f32_e32 v52, v52
	v_rcp_f32_e32 v53, v53
	s_nop 0
	v_pk_mul_f32 v[48:49], v[48:49], v[52:53]
	s_nop 0
	v_pk_mul_f32 v[44:45], v[48:49], v[44:45]
	s_nop 0
	v_cvt_pk_bf16_f32 v44, v44, v45
	v_mul_f32_e32 v45, 0xbfb8aa3b, v50
	v_exp_f32_e32 v45, v45
	s_nop 0
	v_add_f32_e32 v45, 1.0, v45
	v_rcp_f32_e32 v48, v45
	v_mul_f32_e32 v45, 0xbfb8aa3b, v51
	v_exp_f32_e32 v45, v45
	s_nop 0
	v_add_f32_e32 v45, 1.0, v45
	v_rcp_f32_e32 v49, v45
	s_nop 0
	v_pk_mul_f32 v[48:49], v[50:51], v[48:49]
	s_nop 0
	v_pk_mul_f32 v[46:47], v[48:49], v[46:47]
	s_nop 0
	v_cvt_pk_bf16_f32 v45, v46, v47
	v_mul_f32_e32 v46, 0xbfb8aa3b, v40
	v_mul_f32_e32 v47, 0xbfb8aa3b, v41
	v_exp_f32_e32 v46, v46
	v_exp_f32_e32 v47, v47
; DI unsigned cvt_pk_bf16(float lo, float hi) { const f32x2 v = {lo, hi}; const bf16x2_t r = __builtin_convertvector(v, bf16x2_t); return __builtin_bit_cast(unsigned, r); }
; DI float silu_f(float g) { return g * __builtin_amdgcn_rcpf(1.0f + __expf(-g)); }
;   DI void operator()(const f32x4 (&acc)[2][2][4][2], const Unit& u, int wr, int wc, int fr, int fq) const {
;     const int row0 = u.pm * BM + wr * 64 + fr, col0 = u.pn * HALF + wc * 32 + 8 * fq;
; #pragma unroll
;     for (int ai = 0; ai < 2; ++ai)
; #pragma unroll
;       for (int m = 0; m < 4; ++m) {
;         const f32x4 g0 = acc[ai][0][m][0], g1 = acc[ai][0][m][1], u0 = acc[ai][1][m][0], u1 = acc[ai][1][m][1];
;         u32x4 w;
;         w.x = cvt_pk_bf16(silu_f(g0[0]) * u0[0], silu_f(g0[1]) * u0[1]); w.y = cvt_pk_bf16(silu_f(g0[2]) * u0[2], silu_f(g0[3]) * u0[3]);
;         w.z = cvt_pk_bf16(silu_f(g1[0]) * u1[0], silu_f(g1[1]) * u1[1]); w.w = cvt_pk_bf16(silu_f(g1[2]) * u1[2], silu_f(g1[3]) * u1[3]);
;         *(u32x4*)(H + (size_t)(row0 + ai * HALF + m * 16) * DFF + col0) = w;
;       }
	v_add_f32_e32 v46, 1.0, v46
	v_add_f32_e32 v47, 1.0, v47
	v_rcp_f32_e32 v46, v46
	v_rcp_f32_e32 v47, v47
	s_nop 0
	v_pk_mul_f32 v[40:41], v[40:41], v[46:47]
	s_nop 0
	v_pk_mul_f32 v[36:37], v[40:41], v[36:37]
	s_nop 0
	v_cvt_pk_bf16_f32 v46, v36, v37
	v_mul_f32_e32 v36, 0xbfb8aa3b, v42
	v_mul_f32_e32 v37, 0xbfb8aa3b, v43
	v_exp_f32_e32 v36, v36
	v_exp_f32_e32 v37, v37
	v_add_f32_e32 v36, 1.0, v36
	v_add_f32_e32 v37, 1.0, v37
	v_rcp_f32_e32 v36, v36
	v_rcp_f32_e32 v37, v37
	s_nop 0
	v_pk_mul_f32 v[36:37], v[42:43], v[36:37]
	s_nop 0
	v_pk_mul_f32 v[36:37], v[36:37], v[38:39]
	s_nop 0
	v_cvt_pk_bf16_f32 v47, v36, v37
	v_add_u32_e32 v36, 0x90, v146
	v_mad_i64_i32 v[36:37], s[30:31], v36, s3, v[116:117]
	v_lshl_add_u64 v[36:37], v[36:37], 0, v[118:119]
	global_store_dwordx4 v[36:37], v[44:47], off
	v_mul_f32_e32 v36, 0xbfb8aa3b, v32
	v_mul_f32_e32 v37, 0xbfb8aa3b, v33
	v_exp_f32_e32 v36, v36
	v_exp_f32_e32 v37, v37
	v_add_f32_e32 v36, 1.0, v36
	v_add_f32_e32 v37, 1.0, v37
	v_rcp_f32_e32 v36, v36
	v_rcp_f32_e32 v37, v37
	s_nop 0
	v_pk_mul_f32 v[32:33], v[32:33], v[36:37]
	s_nop 0
	v_pk_mul_f32 v[28:29], v[32:33], v[28:29]
	s_nop 0
	v_cvt_pk_bf16_f32 v28, v28, v29
	v_mul_f32_e32 v29, 0xbfb8aa3b, v34
	v_exp_f32_e32 v29, v29
	s_nop 0
	v_add_f32_e32 v29, 1.0, v29
	v_rcp_f32_e32 v32, v29
	v_mul_f32_e32 v29, 0xbfb8aa3b, v35
	v_exp_f32_e32 v29, v29
	s_nop 0
	v_add_f32_e32 v29, 1.0, v29
	v_rcp_f32_e32 v33, v29
	s_nop 0
	v_pk_mul_f32 v[32:33], v[34:35], v[32:33]
	s_nop 0
	v_pk_mul_f32 v[30:31], v[32:33], v[30:31]
	s_nop 0
	v_cvt_pk_bf16_f32 v29, v30, v31
	v_mul_f32_e32 v30, 0xbfb8aa3b, v24
	v_mul_f32_e32 v31, 0xbfb8aa3b, v25
	v_exp_f32_e32 v30, v30
	v_exp_f32_e32 v31, v31
	v_add_f32_e32 v30, 1.0, v30
	v_add_f32_e32 v31, 1.0, v31
	v_rcp_f32_e32 v30, v30
	v_rcp_f32_e32 v31, v31
	s_nop 0
	v_pk_mul_f32 v[24:25], v[24:25], v[30:31]
	s_nop 0
	v_pk_mul_f32 v[20:21], v[24:25], v[20:21]
	s_nop 0
	v_cvt_pk_bf16_f32 v30, v20, v21
	v_mul_f32_e32 v20, 0xbfb8aa3b, v26
	v_mul_f32_e32 v21, 0xbfb8aa3b, v27
	v_exp_f32_e32 v20, v20
	v_exp_f32_e32 v21, v21
	v_add_f32_e32 v20, 1.0, v20
	v_add_f32_e32 v21, 1.0, v21
	v_rcp_f32_e32 v20, v20
	v_rcp_f32_e32 v21, v21
	s_nop 0
	v_pk_mul_f32 v[20:21], v[26:27], v[20:21]
	s_nop 0
	v_pk_mul_f32 v[20:21], v[20:21], v[22:23]
	s_nop 0
	v_cvt_pk_bf16_f32 v31, v20, v21
	v_add_u32_e32 v20, 0xa0, v146
	v_mad_i64_i32 v[20:21], s[30:31], v20, s3, v[116:117]
	v_lshl_add_u64 v[20:21], v[20:21], 0, v[118:119]
	global_store_dwordx4 v[20:21], v[28:31], off
	v_mul_f32_e32 v20, 0xbfb8aa3b, v16
	v_mul_f32_e32 v21, 0xbfb8aa3b, v17
	v_exp_f32_e32 v20, v20
	v_exp_f32_e32 v21, v21
	v_add_f32_e32 v20, 1.0, v20
	v_add_f32_e32 v21, 1.0, v21
	v_rcp_f32_e32 v20, v20
	v_rcp_f32_e32 v21, v21
	s_nop 0
	v_pk_mul_f32 v[16:17], v[16:17], v[20:21]
	s_nop 0
	v_pk_mul_f32 v[12:13], v[16:17], v[12:13]
	s_nop 0
	v_cvt_pk_bf16_f32 v12, v12, v13
	v_mul_f32_e32 v13, 0xbfb8aa3b, v18
	v_exp_f32_e32 v13, v13
	s_nop 0
	v_add_f32_e32 v13, 1.0, v13
	v_rcp_f32_e32 v16, v13
	v_mul_f32_e32 v13, 0xbfb8aa3b, v19
	v_exp_f32_e32 v13, v13
	s_nop 0
	v_add_f32_e32 v13, 1.0, v13
	v_rcp_f32_e32 v17, v13
	s_nop 0
	v_pk_mul_f32 v[16:17], v[18:19], v[16:17]
	s_nop 0
	v_pk_mul_f32 v[14:15], v[16:17], v[14:15]
	s_nop 0
	v_cvt_pk_bf16_f32 v13, v14, v15
	v_mul_f32_e32 v14, 0xbfb8aa3b, v8
	v_mul_f32_e32 v15, 0xbfb8aa3b, v9
	v_exp_f32_e32 v14, v14
	v_exp_f32_e32 v15, v15
	v_add_f32_e32 v14, 1.0, v14
	v_add_f32_e32 v15, 1.0, v15
	v_rcp_f32_e32 v14, v14
	v_rcp_f32_e32 v15, v15
	s_nop 0
	v_pk_mul_f32 v[8:9], v[8:9], v[14:15]
	s_nop 0
	v_pk_mul_f32 v[4:5], v[8:9], v[4:5]
	s_nop 0
	v_cvt_pk_bf16_f32 v14, v4, v5
	v_mul_f32_e32 v4, 0xbfb8aa3b, v10
	v_mul_f32_e32 v5, 0xbfb8aa3b, v11
	v_exp_f32_e32 v4, v4
	v_exp_f32_e32 v5, v5
	v_add_f32_e32 v4, 1.0, v4
	v_add_f32_e32 v5, 1.0, v5
	v_rcp_f32_e32 v4, v4
	v_rcp_f32_e32 v5, v5
	s_nop 0
	v_pk_mul_f32 v[4:5], v[10:11], v[4:5]
	s_nop 0
	v_pk_mul_f32 v[4:5], v[4:5], v[6:7]
	s_nop 0
	v_cvt_pk_bf16_f32 v15, v4, v5
	v_add_u32_e32 v4, 0xb0, v146
	v_mad_i64_i32 v[4:5], s[30:31], v4, s3, v[116:117]
	v_lshl_add_u64 v[4:5], v[4:5], 0, v[118:119]
	s_mov_b64 s[30:31], s[18:19]
	global_store_dwordx4 v[4:5], v[12:15], off
	s_cbranch_vccz .LBB0_187
	s_waitcnt vmcnt(0)
	s_cmpk_gt_u32 s25, 0xff
	s_cbranch_scc1 .LBB0_194
	s_barrier

; #define PG8_WAIT_V(n) asm volatile("s_waitcnt vmcnt(" #n ")" ::: "memory")
; #define PG8_WAIT_L(n) asm volatile("s_waitcnt lgkmcnt(" #n ")" ::: "memory")
; template <class Epi>
; DI void gemm_phase(LAS unsigned char* lds, const Gemm g, const Epi& E) {
;     ...
;   f32x4 acc[2][2][4][2];
; #pragma unroll
;   for (int a = 0; a < 2; ++a)
; #pragma unroll
;     for (int b = 0; b < 2; ++b)
; #pragma unroll
;       for (int m = 0; m < 4; ++m)
; #pragma unroll
;         for (int n = 0; n < 2; ++n) acc[a][b][m][n] = (f32x4){0.f, 0.f, 0.f, 0.f};
;   bf16x8 At[4][2], B0[2][2], B1[2][2];
;     ...
;   const char* cA = PG8_APTR(cur); const char* cB = (const char*)g.Bt + (size_t)cur.pn * tstepB;
;   PG8_STAGE(PG8_SB(0, 0), cB, voffB); PG8_STAGE(PG8_SA(0, 0), cA, voffA); PG8_STAGE(PG8_SB(0, 1), cB + hstepB, voffB); PG8_STAGE(PG8_SA(0, 1), cA + hstepA, voffA);
;   if (wr == 1) PG8_BAR;
;   PG8_WAIT_V(4); PG8_BAR;
;   PG8_STAGE(PG8_SB(1, 0), cB + kstep, voffB); PG8_STAGE(PG8_SA(1, 0), cA + kstep, voffA); PG8_STAGE(PG8_SB(1, 1), cB + hstepB + kstep, voffB);
;   PG8_WAIT_V(6); PG8_BAR;
;   for (;;) {
;     const bool has_next = S.next(ui + 1, nxt);
;     const char* nA = has_next ? PG8_APTR(nxt) : cA; const char* nB = has_next ? (const char*)g.Bt + (size_t)nxt.pn * tstepB : cB;
;     for (int t = 0; t < nt; t += 2) {
;       const bool last = (t == nt - 2);
;       const char* a1 = cA + (size_t)(t + 1) * kstep;
;       const char* a2 = last ? nA : cA + (size_t)(t + 2) * kstep; const char* b2 = last ? nB : cB + (size_t)(t + 2) * kstep;
;       const char* a3 = a2 + kstep; const char* b3 = b2 + kstep;
;       PG8_LDB(B0, 0, 0); PG8_SCHED; PG8_LDA(At, 0, 0); PG8_STAGE(PG8_SA(1, 1), a1 + hstepA, voffA);
;       PG8_WAIT_L(8); PG8_BAR; PG8_WAIT_L(0); PG8_MMA(0, 0, At, B0); PG8_BAR; PG8_SCHED;
;       PG8_LDB(B1, 0, 1); PG8_STAGE(PG8_SB(0, 0), b2, voffB);
;       PG8_BAR; PG8_WAIT_L(0); PG8_MMA(0, 1, At, B1); PG8_BAR;
;       PG8_LDA(At, 0, 1); PG8_STAGE(PG8_SA(0, 0), a2, voffA);
;       PG8_BAR; PG8_WAIT_L(0); PG8_MMA(1, 0, At, B0); PG8_BAR; PG8_SCHED;
;       PG8_STAGE(PG8_SB(0, 1), b2 + hstepB, voffB);
;       PG8_WAIT_V(6); PG8_BAR; PG8_MMA(1, 1, At, B1); PG8_BAR;
;       PG8_LDB(B0, 1, 0); PG8_SCHED; PG8_LDA(At, 1, 0); PG8_STAGE(PG8_SA(0, 1), a2 + hstepA, voffA);
;       PG8_WAIT_L(8); PG8_BAR; PG8_WAIT_L(0); PG8_MMA(0, 0, At, B0); PG8_BAR; PG8_SCHED;
.LBB0_224:
	s_ashr_i32 s27, s26, 31
	v_cmp_lt_i64_e32 vcc, s[30:31], v[174:175]
	s_lshl_b64 s[30:31], s[26:27], 20
	s_add_u32 s30, s49, s30
	s_addc_u32 s31, s50, s31
	s_and_b64 s[36:37], vcc, exec
	s_cselect_b32 s27, s31, s43
	s_cselect_b32 s41, s30, s42
	s_ashr_i32 s23, s22, 31
	s_lshl_b64 s[36:37], s[22:23], 20
	s_add_u32 s36, s51, s36
	s_addc_u32 s37, s52, s37
	s_and_b64 s[46:47], vcc, exec
	s_cselect_b32 s23, s37, s45
	s_cselect_b32 s63, s36, s44
	s_add_u32 s42, s42, 0x80080
	s_addc_u32 s43, s43, 0
	s_add_u32 s64, s44, 0x100
	s_addc_u32 s65, s45, 0
	s_mov_b32 s66, -2
	v_add_u32_e32 v248, 0x10000, v151
	ds_read_b128 v[156:159], v248
	ds_read_b128 v[160:163], v248 offset:1024
	ds_read_b128 v[180:183], v248 offset:2048
	ds_read_b128 v[184:187], v248 offset:3072
	s_add_u32 s44, s42, 0xfff80080
	s_addc_u32 s45, s43, -1
	s_add_i32 s67, 0, 0x10000
	s_cmp_eq_u32 s66, 28
	s_cselect_b32 s47, s27, s45
	s_cselect_b32 s46, s41, s44
	s_cselect_b32 s45, s23, s65
	s_cselect_b32 s44, s63, s64
	s_add_i32 m0, s55, 0xc000
	ds_read_b128 v[188:191], v154
	ds_read_b128 v[192:195], v154 offset:1024
	ds_read_b128 v[196:199], v154 offset:2048
	ds_read_b128 v[200:203], v154 offset:3072
	ds_read_b128 v[208:211], v154 offset:4096
	ds_read_b128 v[212:215], v154 offset:5120
	ds_read_b128 v[216:219], v154 offset:6144
	ds_read_b128 v[220:223], v154 offset:7168
	global_load_lds_dwordx4 v144, s[42:43]
	s_add_i32 m0, s55, 0xe000
	s_nop 0
	global_load_lds_dwordx4 v146, s[42:43]
	s_waitcnt lgkmcnt(8)
	s_barrier
	s_waitcnt lgkmcnt(0)
	s_setprio 1
	s_waitcnt lgkmcnt(0)
	v_mfma_f32_16x16x32_bf16 v[128:131], v[156:159], v[188:191], 0
	v_mfma_f32_16x16x32_bf16 v[124:127], v[180:183], v[188:191], 0
	v_mfma_f32_16x16x32_bf16 v[120:123], v[156:159], v[196:199], 0
	v_mfma_f32_16x16x32_bf16 v[116:119], v[180:183], v[196:199], 0
	v_mfma_f32_16x16x32_bf16 v[104:107], v[156:159], v[208:211], 0
	v_mfma_f32_16x16x32_bf16 v[100:103], v[180:183], v[208:211], 0
	v_mfma_f32_16x16x32_bf16 v[88:91], v[156:159], v[216:219], 0
	v_mfma_f32_16x16x32_bf16 v[84:87], v[180:183], v[216:219], 0
	v_mfma_f32_16x16x32_bf16 v[128:131], v[160:163], v[192:195], v[128:131]
	v_mfma_f32_16x16x32_bf16 v[124:127], v[184:187], v[192:195], v[124:127]
	v_mfma_f32_16x16x32_bf16 v[120:123], v[160:163], v[200:203], v[120:123]
	v_mfma_f32_16x16x32_bf16 v[116:119], v[184:187], v[200:203], v[116:119]
	v_mfma_f32_16x16x32_bf16 v[104:107], v[160:163], v[212:215], v[104:107]
	v_mfma_f32_16x16x32_bf16 v[100:103], v[184:187], v[212:215], v[100:103]
	s_setprio 2
	s_barrier
	v_mfma_f32_16x16x32_bf16 v[88:91], v[160:163], v[220:223], v[88:91]
	v_mfma_f32_16x16x32_bf16 v[84:87], v[184:187], v[220:223], v[84:87]
	s_setprio 0
	s_add_i32 s70, 0, 0x14000
	s_add_i32 s67, s67, s54
	v_lshl_add_u64 v[148:149], s[44:45], 0, v[136:137]
	s_mov_b32 m0, s67
	ds_read_b128 v[224:227], v248 offset:16384
	ds_read_b128 v[228:231], v248 offset:17408
	ds_read_b128 v[232:235], v248 offset:18432
	ds_read_b128 v[236:239], v248 offset:19456
	global_load_lds_dwordx4 v[148:149], off
	v_lshl_add_u64 v[240:241], s[44:45], 0, v[132:133]
	s_add_i32 m0, s67, 0x2000
	s_nop 0
	global_load_lds_dwordx4 v[240:241], off
	s_barrier
	s_waitcnt lgkmcnt(0)
	s_setprio 1
	s_waitcnt lgkmcnt(0)
	v_mfma_f32_16x16x32_bf16 v[112:115], v[224:227], v[188:191], 0
	v_mfma_f32_16x16x32_bf16 v[108:111], v[232:235], v[188:191], 0
	v_mfma_f32_16x16x32_bf16 v[96:99], v[224:227], v[196:199], 0
	v_mfma_f32_16x16x32_bf16 v[92:95], v[232:235], v[196:199], 0
	v_mfma_f32_16x16x32_bf16 v[80:83], v[224:227], v[208:211], 0
	v_mfma_f32_16x16x32_bf16 v[76:79], v[232:235], v[208:211], 0
	v_mfma_f32_16x16x32_bf16 v[72:75], v[224:227], v[216:219], 0
	v_mfma_f32_16x16x32_bf16 v[68:71], v[232:235], v[216:219], 0
	v_mfma_f32_16x16x32_bf16 v[112:115], v[228:231], v[192:195], v[112:115]
	v_mfma_f32_16x16x32_bf16 v[108:111], v[236:239], v[192:195], v[108:111]
	v_mfma_f32_16x16x32_bf16 v[96:99], v[228:231], v[200:203], v[96:99]
	v_mfma_f32_16x16x32_bf16 v[92:95], v[236:239], v[200:203], v[92:95]
	v_mfma_f32_16x16x32_bf16 v[80:83], v[228:231], v[212:215], v[80:83]
	v_mfma_f32_16x16x32_bf16 v[76:79], v[236:239], v[212:215], v[76:79]
	s_setprio 2
	s_barrier
	v_mfma_f32_16x16x32_bf16 v[72:75], v[228:231], v[220:223], v[72:75]
	v_mfma_f32_16x16x32_bf16 v[68:71], v[236:239], v[220:223], v[68:71]
	s_setprio 0
	s_mov_b32 m0, s55
	v_lshl_add_u64 v[242:243], s[46:47], 0, v[138:139]
	ds_read_b128 v[188:191], v154 offset:16384
	ds_read_b128 v[192:195], v154 offset:17408
	ds_read_b128 v[196:199], v154 offset:18432
	ds_read_b128 v[200:203], v154 offset:19456
	ds_read_b128 v[208:211], v154 offset:20480
	ds_read_b128 v[212:215], v154 offset:21504
	ds_read_b128 v[216:219], v154 offset:22528
	ds_read_b128 v[220:223], v154 offset:23552
	global_load_lds_dwordx4 v[242:243], off
	v_lshl_add_u64 v[244:245], s[46:47], 0, v[134:135]
	s_mov_b32 m0, s56
	s_nop 0
	global_load_lds_dwordx4 v[244:245], off
	s_waitcnt vmcnt(10)
	s_barrier
	s_waitcnt lgkmcnt(0)
	s_setprio 1
	s_waitcnt lgkmcnt(0)
	v_mfma_f32_16x16x32_bf16 v[64:67], v[156:159], v[188:191], 0
	v_mfma_f32_16x16x32_bf16 v[60:63], v[180:183], v[188:191], 0
	v_mfma_f32_16x16x32_bf16 v[56:59], v[156:159], v[196:199], 0
	v_mfma_f32_16x16x32_bf16 v[52:55], v[180:183], v[196:199], 0
	v_mfma_f32_16x16x32_bf16 v[40:43], v[156:159], v[208:211], 0
	v_mfma_f32_16x16x32_bf16 v[36:39], v[180:183], v[208:211], 0
	v_mfma_f32_16x16x32_bf16 v[24:27], v[156:159], v[216:219], 0
	v_mfma_f32_16x16x32_bf16 v[20:23], v[180:183], v[216:219], 0
	v_mfma_f32_16x16x32_bf16 v[64:67], v[160:163], v[192:195], v[64:67]
	v_mfma_f32_16x16x32_bf16 v[60:63], v[184:187], v[192:195], v[60:63]
	v_mfma_f32_16x16x32_bf16 v[56:59], v[160:163], v[200:203], v[56:59]
	v_mfma_f32_16x16x32_bf16 v[52:55], v[184:187], v[200:203], v[52:55]
	v_mfma_f32_16x16x32_bf16 v[40:43], v[160:163], v[212:215], v[40:43]
	v_mfma_f32_16x16x32_bf16 v[36:39], v[184:187], v[212:215], v[36:39]
	s_setprio 2
	s_barrier
; #define PG8_STAGE(bufoff, gbase, voff) do { _Pragma("unroll") for (int _i = 0; _i < 2; ++_i) \
;     __builtin_amdgcn_global_load_lds((const unsigned*)((const char*)(gbase) + (voff)[_i]), (LAS unsigned*)(lds + (bufoff) + ldsw + _i * 8192), 16, 0, 0); } while (0)
; #define PG8_LDA(dst, b, h) do { _Pragma("unroll") for (int m = 0; m < 4; ++m) _Pragma("unroll") for (int k = 0; k < 2; ++k) dst[m][k] = *(const LAS bf16x8*)(lds + PG8_SA(b, h) + aoff + m * 2048 + k * 1024); } while (0)
; #define PG8_LDB(dst, b, h) do { _Pragma("unroll") for (int n = 0; n < 2; ++n) _Pragma("unroll") for (int k = 0; k < 2; ++k) dst[n][k] = *(const LAS bf16x8*)(lds + PG8_SB(b, h) + boff + n * 2048 + k * 1024); } while (0)
; #define PG8_MMA(ai, bj, At, Bt) do { __builtin_amdgcn_s_setprio(1); _Pragma("unroll") for (int m = 0; m < 4; ++m) _Pragma("unroll") for (int n = 0; n < 2; ++n) _Pragma("unroll") for (int k = 0; k < 2; ++k) \
;     acc[ai][bj][m][n] = __builtin_amdgcn_mfma_f32_16x16x32_bf16(Bt[n][k], At[m][k], acc[ai][bj][m][n], 0, 0, 0); __builtin_amdgcn_s_setprio(0); } while (0)
; #define PG8_WAIT_V(n) asm volatile("s_waitcnt vmcnt(" #n ")" ::: "memory")
; #define PG8_WAIT_L(n) asm volatile("s_waitcnt lgkmcnt(" #n ")" ::: "memory")
; #define PG8_BAR __builtin_amdgcn_s_barrier()
; #define PG8_SCHED __builtin_amdgcn_sched_barrier(0)
; template <class Epi>
; DI void gemm_phase(LAS unsigned char* lds, const Gemm g, const Epi& E) {
;     ...
;       PG8_BAR; PG8_WAIT_L(0); PG8_MMA(1, 0, At, B0); PG8_BAR; PG8_SCHED;
;       PG8_STAGE(PG8_SB(0, 1), b2 + hstepB, voffB);
;       PG8_WAIT_V(6); PG8_BAR; PG8_MMA(1, 1, At, B1); PG8_BAR;
;       PG8_LDB(B0, 1, 0); PG8_SCHED; PG8_LDA(At, 1, 0); PG8_STAGE(PG8_SA(0, 1), a2 + hstepA, voffA);
;       PG8_WAIT_L(8); PG8_BAR; PG8_WAIT_L(0); PG8_MMA(0, 0, At, B0); PG8_BAR; PG8_SCHED;
;       PG8_LDB(B1, 1, 1); PG8_STAGE(PG8_SB(1, 0), b3, voffB);
;       PG8_BAR; PG8_WAIT_L(0); PG8_MMA(0, 1, At, B1); PG8_BAR;
	v_mfma_f32_16x16x32_bf16 v[24:27], v[160:163], v[220:223], v[24:27]
	v_mfma_f32_16x16x32_bf16 v[20:23], v[184:187], v[220:223], v[20:23]
	s_setprio 0
	ds_read_b128 v[156:159], v248 offset:32768
	ds_read_b128 v[160:163], v248 offset:33792
	ds_read_b128 v[180:183], v248 offset:34816
	ds_read_b128 v[184:187], v248 offset:35840
	s_add_u32 s68, s44, 0x80000
	s_addc_u32 s69, s45, 0
	s_add_i32 s67, s70, s54
	s_mov_b32 m0, s67
	s_nop 0
	global_load_lds_dwordx4 v136, s[68:69]
	s_add_i32 m0, s67, 0x2000
	s_nop 0
	global_load_lds_dwordx4 v132, s[68:69]
	s_waitcnt vmcnt(6)
	s_barrier
	s_setprio 1
	v_mfma_f32_16x16x32_bf16 v[48:51], v[224:227], v[188:191], 0
	v_mfma_f32_16x16x32_bf16 v[44:47], v[232:235], v[188:191], 0
	v_mfma_f32_16x16x32_bf16 v[32:35], v[224:227], v[196:199], 0
	v_mfma_f32_16x16x32_bf16 v[28:31], v[232:235], v[196:199], 0
	v_mfma_f32_16x16x32_bf16 v[16:19], v[224:227], v[208:211], 0
	v_mfma_f32_16x16x32_bf16 v[12:15], v[232:235], v[208:211], 0
	v_mfma_f32_16x16x32_bf16 v[8:11], v[224:227], v[216:219], 0
	v_mfma_f32_16x16x32_bf16 v[4:7], v[232:235], v[216:219], 0
	v_mfma_f32_16x16x32_bf16 v[48:51], v[228:231], v[192:195], v[48:51]
	v_mfma_f32_16x16x32_bf16 v[44:47], v[236:239], v[192:195], v[44:47]
	v_mfma_f32_16x16x32_bf16 v[32:35], v[228:231], v[200:203], v[32:35]
	v_mfma_f32_16x16x32_bf16 v[28:31], v[236:239], v[200:203], v[28:31]
	v_mfma_f32_16x16x32_bf16 v[16:19], v[228:231], v[212:215], v[16:19]
	v_mfma_f32_16x16x32_bf16 v[12:15], v[236:239], v[212:215], v[12:15]
	s_setprio 2
	s_barrier
	v_mfma_f32_16x16x32_bf16 v[8:11], v[228:231], v[220:223], v[8:11]
	v_mfma_f32_16x16x32_bf16 v[4:7], v[236:239], v[220:223], v[4:7]
	s_setprio 0
	s_add_i32 s67, 0, 0x18000
	s_add_u32 s46, s46, 0x80000
	s_addc_u32 s47, s47, 0
	s_mov_b32 m0, s57
	ds_read_b128 v[188:191], v154 offset:32768
	ds_read_b128 v[192:195], v154 offset:33792
	ds_read_b128 v[196:199], v154 offset:34816
	ds_read_b128 v[200:203], v154 offset:35840
	ds_read_b128 v[208:211], v154 offset:36864
	ds_read_b128 v[212:215], v154 offset:37888
	ds_read_b128 v[216:219], v154 offset:38912
	ds_read_b128 v[220:223], v154 offset:39936
	global_load_lds_dwordx4 v138, s[46:47]
	s_mov_b32 m0, s58
	s_nop 0
	global_load_lds_dwordx4 v134, s[46:47]
	s_waitcnt lgkmcnt(8)
	s_barrier
	s_waitcnt lgkmcnt(0)
	s_setprio 1
	s_waitcnt lgkmcnt(0)
	v_mfma_f32_16x16x32_bf16 v[128:131], v[156:159], v[188:191], v[128:131]
	v_mfma_f32_16x16x32_bf16 v[124:127], v[180:183], v[188:191], v[124:127]
	v_mfma_f32_16x16x32_bf16 v[120:123], v[156:159], v[196:199], v[120:123]
	v_mfma_f32_16x16x32_bf16 v[116:119], v[180:183], v[196:199], v[116:119]
	v_mfma_f32_16x16x32_bf16 v[104:107], v[156:159], v[208:211], v[104:107]
	v_mfma_f32_16x16x32_bf16 v[100:103], v[180:183], v[208:211], v[100:103]
	v_mfma_f32_16x16x32_bf16 v[88:91], v[156:159], v[216:219], v[88:91]
	v_mfma_f32_16x16x32_bf16 v[84:87], v[180:183], v[216:219], v[84:87]
	v_mfma_f32_16x16x32_bf16 v[128:131], v[160:163], v[192:195], v[128:131]
	v_mfma_f32_16x16x32_bf16 v[124:127], v[184:187], v[192:195], v[124:127]
	v_mfma_f32_16x16x32_bf16 v[120:123], v[160:163], v[200:203], v[120:123]
	v_mfma_f32_16x16x32_bf16 v[116:119], v[184:187], v[200:203], v[116:119]
	v_mfma_f32_16x16x32_bf16 v[104:107], v[160:163], v[212:215], v[104:107]
	v_mfma_f32_16x16x32_bf16 v[100:103], v[184:187], v[212:215], v[100:103]
	s_setprio 2
	s_barrier
	v_mfma_f32_16x16x32_bf16 v[88:91], v[160:163], v[220:223], v[88:91]
	v_mfma_f32_16x16x32_bf16 v[84:87], v[184:187], v[220:223], v[84:87]
	s_setprio 0
	s_add_i32 s46, 0, 0x1c000
	s_add_i32 s47, s67, s54
	v_lshl_add_u64 v[148:149], v[148:149], 0, s[84:85]
	s_mov_b32 m0, s47
	ds_read_b128 v[224:227], v248 offset:49152
	ds_read_b128 v[228:231], v248 offset:50176
	ds_read_b128 v[232:235], v248 offset:51200
	ds_read_b128 v[236:239], v248 offset:52224
	global_load_lds_dwordx4 v[148:149], off
	v_lshl_add_u64 v[148:149], v[240:241], 0, s[84:85]
	s_add_i32 m0, s47, 0x2000
	s_nop 0
	global_load_lds_dwordx4 v[148:149], off
	s_barrier
; #define PG8_STAGE(bufoff, gbase, voff) do { _Pragma("unroll") for (int _i = 0; _i < 2; ++_i) \
;     __builtin_amdgcn_global_load_lds((const unsigned*)((const char*)(gbase) + (voff)[_i]), (LAS unsigned*)(lds + (bufoff) + ldsw + _i * 8192), 16, 0, 0); } while (0)
; #define PG8_LDA(dst, b, h) do { _Pragma("unroll") for (int m = 0; m < 4; ++m) _Pragma("unroll") for (int k = 0; k < 2; ++k) dst[m][k] = *(const LAS bf16x8*)(lds + PG8_SA(b, h) + aoff + m * 2048 + k * 1024); } while (0)
; #define PG8_MMA(ai, bj, At, Bt) do { __builtin_amdgcn_s_setprio(1); _Pragma("unroll") for (int m = 0; m < 4; ++m) _Pragma("unroll") for (int n = 0; n < 2; ++n) _Pragma("unroll") for (int k = 0; k < 2; ++k) \
;     acc[ai][bj][m][n] = __builtin_amdgcn_mfma_f32_16x16x32_bf16(Bt[n][k], At[m][k], acc[ai][bj][m][n], 0, 0, 0); __builtin_amdgcn_s_setprio(0); } while (0)
; #define PG8_WAIT_V(n) asm volatile("s_waitcnt vmcnt(" #n ")" ::: "memory")
; #define PG8_WAIT_L(n) asm volatile("s_waitcnt lgkmcnt(" #n ")" ::: "memory")
; #define PG8_BAR __builtin_amdgcn_s_barrier()
; #define PG8_SCHED __builtin_amdgcn_sched_barrier(0)
; template <class Epi>
; DI void gemm_phase(LAS unsigned char* lds, const Gemm g, const Epi& E) {
;     ...
;       PG8_BAR; PG8_WAIT_L(0); PG8_MMA(0, 1, At, B1); PG8_BAR;
;       PG8_LDA(At, 1, 1); PG8_STAGE(PG8_SA(1, 0), a3, voffA);
;       PG8_BAR; PG8_WAIT_L(0); PG8_MMA(1, 0, At, B0); PG8_BAR; PG8_SCHED;
;       PG8_STAGE(PG8_SB(1, 1), b3 + hstepB, voffB);
;       PG8_WAIT_V(6); PG8_BAR; PG8_MMA(1, 1, At, B1); PG8_BAR;
	s_waitcnt lgkmcnt(0)
	s_setprio 1
	s_waitcnt lgkmcnt(0)
	v_mfma_f32_16x16x32_bf16 v[112:115], v[224:227], v[188:191], v[112:115]
	v_mfma_f32_16x16x32_bf16 v[108:111], v[232:235], v[188:191], v[108:111]
	v_mfma_f32_16x16x32_bf16 v[96:99], v[224:227], v[196:199], v[96:99]
	v_mfma_f32_16x16x32_bf16 v[92:95], v[232:235], v[196:199], v[92:95]
	v_mfma_f32_16x16x32_bf16 v[80:83], v[224:227], v[208:211], v[80:83]
	v_mfma_f32_16x16x32_bf16 v[76:79], v[232:235], v[208:211], v[76:79]
	v_mfma_f32_16x16x32_bf16 v[72:75], v[224:227], v[216:219], v[72:75]
	v_mfma_f32_16x16x32_bf16 v[68:71], v[232:235], v[216:219], v[68:71]
	v_mfma_f32_16x16x32_bf16 v[112:115], v[228:231], v[192:195], v[112:115]
	v_mfma_f32_16x16x32_bf16 v[108:111], v[236:239], v[192:195], v[108:111]
	v_mfma_f32_16x16x32_bf16 v[96:99], v[228:231], v[200:203], v[96:99]
	v_mfma_f32_16x16x32_bf16 v[92:95], v[236:239], v[200:203], v[92:95]
	v_mfma_f32_16x16x32_bf16 v[80:83], v[228:231], v[212:215], v[80:83]
	v_mfma_f32_16x16x32_bf16 v[76:79], v[236:239], v[212:215], v[76:79]
	s_setprio 2
	s_barrier
	v_mfma_f32_16x16x32_bf16 v[72:75], v[228:231], v[220:223], v[72:75]
	v_mfma_f32_16x16x32_bf16 v[68:71], v[236:239], v[220:223], v[68:71]
	s_setprio 0
	s_mov_b32 m0, s60
	v_lshl_add_u64 v[148:149], v[242:243], 0, s[84:85]
	ds_read_b128 v[188:191], v154 offset:49152
	ds_read_b128 v[192:195], v154 offset:50176
	ds_read_b128 v[196:199], v154 offset:51200
	ds_read_b128 v[200:203], v154 offset:52224
	ds_read_b128 v[208:211], v154 offset:53248
	ds_read_b128 v[212:215], v154 offset:54272
	ds_read_b128 v[216:219], v154 offset:55296
	ds_read_b128 v[220:223], v154 offset:56320
	global_load_lds_dwordx4 v[148:149], off
	v_lshl_add_u64 v[148:149], v[244:245], 0, s[84:85]
	s_mov_b32 m0, s61
	s_nop 0
	global_load_lds_dwordx4 v[148:149], off
	s_waitcnt vmcnt(10)
	s_barrier
	s_waitcnt lgkmcnt(0)
	s_setprio 1
	s_waitcnt lgkmcnt(0)
	v_mfma_f32_16x16x32_bf16 v[64:67], v[156:159], v[188:191], v[64:67]
	v_mfma_f32_16x16x32_bf16 v[60:63], v[180:183], v[188:191], v[60:63]
	v_mfma_f32_16x16x32_bf16 v[56:59], v[156:159], v[196:199], v[56:59]
	v_mfma_f32_16x16x32_bf16 v[52:55], v[180:183], v[196:199], v[52:55]
	v_mfma_f32_16x16x32_bf16 v[40:43], v[156:159], v[208:211], v[40:43]
	v_mfma_f32_16x16x32_bf16 v[36:39], v[180:183], v[208:211], v[36:39]
	v_mfma_f32_16x16x32_bf16 v[24:27], v[156:159], v[216:219], v[24:27]
	v_mfma_f32_16x16x32_bf16 v[20:23], v[180:183], v[216:219], v[20:23]
	v_mfma_f32_16x16x32_bf16 v[64:67], v[160:163], v[192:195], v[64:67]
	v_mfma_f32_16x16x32_bf16 v[60:63], v[184:187], v[192:195], v[60:63]
	v_mfma_f32_16x16x32_bf16 v[56:59], v[160:163], v[200:203], v[56:59]
	v_mfma_f32_16x16x32_bf16 v[52:55], v[184:187], v[200:203], v[52:55]
	v_mfma_f32_16x16x32_bf16 v[40:43], v[160:163], v[212:215], v[40:43]
	v_mfma_f32_16x16x32_bf16 v[36:39], v[184:187], v[212:215], v[36:39]
	s_setprio 2
	s_barrier
	v_mfma_f32_16x16x32_bf16 v[24:27], v[160:163], v[220:223], v[24:27]
	v_mfma_f32_16x16x32_bf16 v[20:23], v[184:187], v[220:223], v[20:23]
	s_setprio 0
	ds_read_b128 v[156:159], v248
	ds_read_b128 v[160:163], v248 offset:1024
	ds_read_b128 v[180:183], v248 offset:2048
	ds_read_b128 v[184:187], v248 offset:3072
	s_add_u32 s44, s44, 0x80080
	s_addc_u32 s45, s45, 0
	s_add_i32 s46, s46, s54
	s_mov_b32 m0, s46
	s_nop 0
	global_load_lds_dwordx4 v136, s[44:45]
	s_add_i32 m0, s46, 0x2000
	s_nop 0
	global_load_lds_dwordx4 v132, s[44:45]
	s_waitcnt vmcnt(6)
	s_barrier
	s_setprio 1
	v_mfma_f32_16x16x32_bf16 v[48:51], v[224:227], v[188:191], v[48:51]
	v_mfma_f32_16x16x32_bf16 v[44:47], v[232:235], v[188:191], v[44:47]
	v_mfma_f32_16x16x32_bf16 v[32:35], v[224:227], v[196:199], v[32:35]
	v_mfma_f32_16x16x32_bf16 v[28:31], v[232:235], v[196:199], v[28:31]
	v_mfma_f32_16x16x32_bf16 v[16:19], v[224:227], v[208:211], v[16:19]
	v_mfma_f32_16x16x32_bf16 v[12:15], v[232:235], v[208:211], v[12:15]
	v_mfma_f32_16x16x32_bf16 v[8:11], v[224:227], v[216:219], v[8:11]
	v_mfma_f32_16x16x32_bf16 v[4:7], v[232:235], v[216:219], v[4:7]
	v_mfma_f32_16x16x32_bf16 v[48:51], v[228:231], v[192:195], v[48:51]
	v_mfma_f32_16x16x32_bf16 v[44:47], v[236:239], v[192:195], v[44:47]
	v_mfma_f32_16x16x32_bf16 v[32:35], v[228:231], v[200:203], v[32:35]
	v_mfma_f32_16x16x32_bf16 v[28:31], v[236:239], v[200:203], v[28:31]
	v_mfma_f32_16x16x32_bf16 v[16:19], v[228:231], v[212:215], v[16:19]
	v_mfma_f32_16x16x32_bf16 v[12:15], v[236:239], v[212:215], v[12:15]
	s_setprio 2
	s_barrier
	v_mfma_f32_16x16x32_bf16 v[8:11], v[228:231], v[220:223], v[8:11]
	v_mfma_f32_16x16x32_bf16 v[4:7], v[236:239], v[220:223], v[4:7]
	s_setprio 0
	s_add_i32 s66, s66, 2
	s_add_u32 s42, s42, 0x100
	s_addc_u32 s43, s43, 0
	s_add_u32 s64, s64, 0x100
	s_addc_u32 s65, s65, 0
	s_cmp_gt_u32 s66, 29
	s_cbranch_scc1 .Lpeel_exit_225

;   DI void operator()(const f32x4 (&acc)[2][2][4][2], const Unit& u, int wr, int wc, int fr, int fq) const {
;     const int row0 = u.pm * BM + wr * 64 + fr; const int pn = u.pn;
;     if (pn < 8 || (pn >= 16 && pn < 24)) {
;     ...
;     } else {
;       if (wc == 0) {
; #pragma unroll
;         for (int ai = 0; ai < 2; ++ai)
; #pragma unroll
;           for (int m = 0; m < 4; ++m) {
;             float* zp = Z + (size_t)(row0 + ai * HALF + m * 16) * 32 + 8 * fq;
;             *(f32x4*)(zp) = acc[ai][0][m][0]; *(f32x4*)(zp + 4) = acc[ai][0][m][1];
;           }
.Lpeel_exit_225:
	s_waitcnt lgkmcnt(0)
	s_lshl_b32 s23, s40, 8
	s_add_i32 s23, s23, s59
	s_cmp_gt_i32 s62, 7
	s_cselect_b64 s[40:41], -1, 0
	s_and_b32 s27, s62, 0x7ffffff8
	s_cmp_lg_u32 s27, 16
	s_cselect_b64 s[42:43], -1, 0
	s_and_b64 s[44:45], s[40:41], s[42:43]
	v_or_b32_e32 v148, s23, v150
	s_mov_b64 s[42:43], -1
	s_and_b64 vcc, exec, s[44:45]
	s_cbranch_vccz .LBB0_234
	s_cmp_gt_u32 s62, 15
	s_cbranch_scc0 .LBB0_231
	s_andn2_b64 vcc, exec, s[18:19]
	s_cbranch_vccnz .LBB0_230
	v_or_b32_e32 v158, 16, v148
	v_ashrrev_i32_e32 v149, 31, v148
	v_ashrrev_i32_e32 v159, 31, v158
	v_lshlrev_b64 v[156:157], 7, v[148:149]
	v_lshlrev_b64 v[158:159], 7, v[158:159]
	v_lshl_add_u64 v[156:157], v[140:141], 0, v[156:157]
	v_lshl_add_u64 v[158:159], v[140:141], 0, v[158:159]
	global_store_dwordx4 v[156:157], v[128:131], off
	global_store_dwordx4 v[156:157], v[124:127], off offset:16
	global_store_dwordx4 v[158:159], v[120:123], off
	global_store_dwordx4 v[158:159], v[116:119], off offset:16
	v_or_b32_e32 v158, 32, v148
	v_ashrrev_i32_e32 v159, 31, v158
	v_lshlrev_b64 v[158:159], 7, v[158:159]
	v_lshl_add_u64 v[158:159], v[140:141], 0, v[158:159]
	global_store_dwordx4 v[158:159], v[104:107], off
	global_store_dwordx4 v[158:159], v[100:103], off offset:16
	v_or_b32_e32 v158, 48, v148
	v_ashrrev_i32_e32 v159, 31, v158
	v_lshlrev_b64 v[158:159], 7, v[158:159]
	s_movk_i32 s27, 0x4000
	v_lshl_add_u64 v[158:159], v[140:141], 0, v[158:159]
	s_mov_b64 s[42:43], 0x4000
	v_add_co_u32_e32 v160, vcc, s27, v156
	global_store_dwordx4 v[158:159], v[88:91], off
	global_store_dwordx4 v[158:159], v[84:87], off offset:16
	v_lshl_add_u64 v[158:159], v[156:157], 0, s[42:43]
	v_addc_co_u32_e32 v161, vcc, 0, v157, vcc
	s_mov_b64 s[42:43], 0x4800
	global_store_dwordx4 v[160:161], v[64:67], off
	global_store_dwordx4 v[158:159], v[60:63], off offset:16
	v_lshl_add_u64 v[158:159], v[156:157], 0, s[42:43]
	global_store_dwordx4 v[160:161], v[56:59], off offset:2048
	global_store_dwordx4 v[158:159], v[52:55], off offset:16
	s_mov_b64 s[42:43], 0x5000
	v_add_co_u32_e32 v160, vcc, 0x5000, v156
	v_lshl_add_u64 v[158:159], v[156:157], 0, s[42:43]
	s_nop 0
	v_addc_co_u32_e32 v161, vcc, 0, v157, vcc
	s_mov_b64 s[42:43], 0x5800
	global_store_dwordx4 v[160:161], v[40:43], off
	global_store_dwordx4 v[158:159], v[36:39], off offset:16
	v_lshl_add_u64 v[156:157], v[156:157], 0, s[42:43]
	global_store_dwordx4 v[160:161], v[24:27], off offset:2048
	global_store_dwordx4 v[156:157], v[20:23], off offset:16

; #define PG8_WAIT_V(n) asm volatile("s_waitcnt vmcnt(" #n ")" ::: "memory")
; #define PG8_WAIT_L(n) asm volatile("s_waitcnt lgkmcnt(" #n ")" ::: "memory")
; template <class Epi>
; DI void gemm_phase(LAS unsigned char* lds, const Gemm g, const Epi& E) {
;     ...
;   f32x4 acc[2][2][4][2];
; #pragma unroll
;   for (int a = 0; a < 2; ++a)
; #pragma unroll
;     for (int b = 0; b < 2; ++b)
; #pragma unroll
;       for (int m = 0; m < 4; ++m)
; #pragma unroll
;         for (int n = 0; n < 2; ++n) acc[a][b][m][n] = (f32x4){0.f, 0.f, 0.f, 0.f};
;   bf16x8 At[4][2], B0[2][2], B1[2][2];
;     ...
;   const char* cA = PG8_APTR(cur); const char* cB = (const char*)g.Bt + (size_t)cur.pn * tstepB;
;   PG8_STAGE(PG8_SB(0, 0), cB, voffB); PG8_STAGE(PG8_SA(0, 0), cA, voffA); PG8_STAGE(PG8_SB(0, 1), cB + hstepB, voffB); PG8_STAGE(PG8_SA(0, 1), cA + hstepA, voffA);
;   if (wr == 1) PG8_BAR;
;   PG8_WAIT_V(4); PG8_BAR;
;   PG8_STAGE(PG8_SB(1, 0), cB + kstep, voffB); PG8_STAGE(PG8_SA(1, 0), cA + kstep, voffA); PG8_STAGE(PG8_SB(1, 1), cB + hstepB + kstep, voffB);
;   PG8_WAIT_V(6); PG8_BAR;
;   for (;;) {
;     const bool has_next = S.next(ui + 1, nxt);
;     const char* nA = has_next ? PG8_APTR(nxt) : cA; const char* nB = has_next ? (const char*)g.Bt + (size_t)nxt.pn * tstepB : cB;
;     for (int t = 0; t < nt; t += 2) {
;       const bool last = (t == nt - 2);
;       const char* a1 = cA + (size_t)(t + 1) * kstep;
;       const char* a2 = last ? nA : cA + (size_t)(t + 2) * kstep; const char* b2 = last ? nB : cB + (size_t)(t + 2) * kstep;
;       const char* a3 = a2 + kstep; const char* b3 = b2 + kstep;
;       PG8_LDB(B0, 0, 0); PG8_SCHED; PG8_LDA(At, 0, 0); PG8_STAGE(PG8_SA(1, 1), a1 + hstepA, voffA);
;       PG8_WAIT_L(8); PG8_BAR; PG8_WAIT_L(0); PG8_MMA(0, 0, At, B0); PG8_BAR; PG8_SCHED;
;       PG8_LDB(B1, 0, 1); PG8_STAGE(PG8_SB(0, 0), b2, voffB);
;       PG8_BAR; PG8_WAIT_L(0); PG8_MMA(0, 1, At, B1); PG8_BAR;
;       PG8_LDA(At, 0, 1); PG8_STAGE(PG8_SA(0, 0), a2, voffA);
;       PG8_BAR; PG8_WAIT_L(0); PG8_MMA(1, 0, At, B0); PG8_BAR; PG8_SCHED;
;       PG8_STAGE(PG8_SB(0, 1), b2 + hstepB, voffB);
;       PG8_WAIT_V(6); PG8_BAR; PG8_MMA(1, 1, At, B1); PG8_BAR;
;       PG8_LDB(B0, 1, 0); PG8_SCHED; PG8_LDA(At, 1, 0); PG8_STAGE(PG8_SA(0, 1), a2 + hstepA, voffA);
;       PG8_WAIT_L(8); PG8_BAR; PG8_WAIT_L(0); PG8_MMA(0, 0, At, B0); PG8_BAR; PG8_SCHED;
.LBB0_513:
	s_add_u32 s42, s58, 0x80
	s_addc_u32 s43, s59, 0
	s_add_u32 s58, s56, 0x100
	s_addc_u32 s59, s57, 0
	s_mov_b32 s44, 0
	v_add_u32_e32 v248, 0x10000, v193
	ds_read_b128 v[132:135], v248
	ds_read_b128 v[136:139], v248 offset:1024
	ds_read_b128 v[140:143], v248 offset:2048
	ds_read_b128 v[144:147], v248 offset:3072
	s_add_i32 s78, s44, 2
	s_add_u32 s56, s42, 0x80
	s_addc_u32 s45, s43, 0
	s_add_i32 s79, 0, 0x10000
	s_cmp_eq_u32 s72, s44
	s_cselect_b32 s44, s52, s56
	s_cselect_b32 s45, s53, s45
	s_cselect_b32 s57, s55, s59
	s_cselect_b32 s56, s54, s58
	s_add_i32 m0, s64, 0xc000
	ds_read_b128 v[148:151], v195
	ds_read_b128 v[152:155], v195 offset:1024
	ds_read_b128 v[156:159], v195 offset:2048
	ds_read_b128 v[160:163], v195 offset:3072
	ds_read_b128 v[196:199], v195 offset:4096
	ds_read_b128 v[200:203], v195 offset:5120
	ds_read_b128 v[208:211], v195 offset:6144
	ds_read_b128 v[212:215], v195 offset:7168
	global_load_lds_dwordx4 v186, s[42:43]
	s_add_i32 m0, s64, 0xe000
	s_nop 0
	global_load_lds_dwordx4 v188, s[42:43]
	s_waitcnt lgkmcnt(8)
	s_barrier
	s_waitcnt lgkmcnt(0)
	s_setprio 1
	s_waitcnt lgkmcnt(0)
	v_mfma_f32_16x16x32_bf16 v[128:131], v[132:135], v[148:151], 0
	v_mfma_f32_16x16x32_bf16 v[124:127], v[140:143], v[148:151], 0
	v_mfma_f32_16x16x32_bf16 v[116:119], v[132:135], v[156:159], 0
	v_mfma_f32_16x16x32_bf16 v[108:111], v[140:143], v[156:159], 0
	v_mfma_f32_16x16x32_bf16 v[100:103], v[132:135], v[196:199], 0
	v_mfma_f32_16x16x32_bf16 v[92:95], v[140:143], v[196:199], 0
	v_mfma_f32_16x16x32_bf16 v[84:87], v[132:135], v[208:211], 0
	v_mfma_f32_16x16x32_bf16 v[76:79], v[140:143], v[208:211], 0
	v_mfma_f32_16x16x32_bf16 v[128:131], v[136:139], v[152:155], v[128:131]
	v_mfma_f32_16x16x32_bf16 v[124:127], v[144:147], v[152:155], v[124:127]
	v_mfma_f32_16x16x32_bf16 v[116:119], v[136:139], v[160:163], v[116:119]
	v_mfma_f32_16x16x32_bf16 v[108:111], v[144:147], v[160:163], v[108:111]
	v_mfma_f32_16x16x32_bf16 v[100:103], v[136:139], v[200:203], v[100:103]
	v_mfma_f32_16x16x32_bf16 v[92:95], v[144:147], v[200:203], v[92:95]
	s_setprio 2
	s_barrier
	v_mfma_f32_16x16x32_bf16 v[84:87], v[136:139], v[212:215], v[84:87]
	v_mfma_f32_16x16x32_bf16 v[76:79], v[144:147], v[212:215], v[76:79]
	s_setprio 0
	s_add_i32 s80, 0, 0x14000
	s_add_i32 s79, s79, s63
	ds_read_b128 v[216:219], v248 offset:16384
	ds_read_b128 v[220:223], v248 offset:17408
	ds_read_b128 v[224:227], v248 offset:18432
	ds_read_b128 v[228:231], v248 offset:19456
	v_lshl_add_u64 v[190:191], s[56:57], 0, v[2:3]
	s_mov_b32 m0, s79
	v_lshl_add_u64 v[232:233], s[56:57], 0, v[184:185]
	global_load_lds_dwordx4 v[190:191], off
	s_add_i32 m0, s79, 0x2000
	s_nop 0
	global_load_lds_dwordx4 v[232:233], off
	s_barrier
	s_waitcnt lgkmcnt(0)
	s_setprio 1
	s_waitcnt lgkmcnt(0)
	v_mfma_f32_16x16x32_bf16 v[120:123], v[216:219], v[148:151], 0
	v_mfma_f32_16x16x32_bf16 v[112:115], v[224:227], v[148:151], 0
	v_mfma_f32_16x16x32_bf16 v[104:107], v[216:219], v[156:159], 0
	v_mfma_f32_16x16x32_bf16 v[96:99], v[224:227], v[156:159], 0
	v_mfma_f32_16x16x32_bf16 v[88:91], v[216:219], v[196:199], 0
	v_mfma_f32_16x16x32_bf16 v[80:83], v[224:227], v[196:199], 0
	v_mfma_f32_16x16x32_bf16 v[72:75], v[216:219], v[208:211], 0
	v_mfma_f32_16x16x32_bf16 v[68:71], v[224:227], v[208:211], 0
	v_mfma_f32_16x16x32_bf16 v[120:123], v[220:223], v[152:155], v[120:123]
	v_mfma_f32_16x16x32_bf16 v[112:115], v[228:231], v[152:155], v[112:115]
	v_mfma_f32_16x16x32_bf16 v[104:107], v[220:223], v[160:163], v[104:107]
	v_mfma_f32_16x16x32_bf16 v[96:99], v[228:231], v[160:163], v[96:99]
	v_mfma_f32_16x16x32_bf16 v[88:91], v[220:223], v[200:203], v[88:91]
	v_mfma_f32_16x16x32_bf16 v[80:83], v[228:231], v[200:203], v[80:83]
	s_setprio 2
	s_barrier
	v_mfma_f32_16x16x32_bf16 v[72:75], v[220:223], v[212:215], v[72:75]
	v_mfma_f32_16x16x32_bf16 v[68:71], v[228:231], v[212:215], v[68:71]
	s_setprio 0
	s_mov_b32 m0, s64
	v_lshl_add_u64 v[234:235], s[44:45], 0, v[180:181]
	ds_read_b128 v[148:151], v195 offset:16384
	ds_read_b128 v[152:155], v195 offset:17408
	ds_read_b128 v[156:159], v195 offset:18432
	ds_read_b128 v[160:163], v195 offset:19456
	ds_read_b128 v[196:199], v195 offset:20480
	ds_read_b128 v[200:203], v195 offset:21504
	ds_read_b128 v[208:211], v195 offset:22528
	ds_read_b128 v[212:215], v195 offset:23552
	global_load_lds_dwordx4 v[234:235], off
	v_lshl_add_u64 v[236:237], s[44:45], 0, v[182:183]
	s_mov_b32 m0, s65
	s_nop 0
	global_load_lds_dwordx4 v[236:237], off
	s_waitcnt vmcnt(10)
	s_barrier
	s_waitcnt lgkmcnt(0)
	s_setprio 1
	s_waitcnt lgkmcnt(0)
	v_mfma_f32_16x16x32_bf16 v[64:67], v[132:135], v[148:151], 0
	v_mfma_f32_16x16x32_bf16 v[60:63], v[140:143], v[148:151], 0
	v_mfma_f32_16x16x32_bf16 v[56:59], v[132:135], v[156:159], 0
	v_mfma_f32_16x16x32_bf16 v[48:51], v[140:143], v[156:159], 0
	v_mfma_f32_16x16x32_bf16 v[40:43], v[132:135], v[196:199], 0
	v_mfma_f32_16x16x32_bf16 v[32:35], v[140:143], v[196:199], 0
	v_mfma_f32_16x16x32_bf16 v[24:27], v[132:135], v[208:211], 0
	v_mfma_f32_16x16x32_bf16 v[16:19], v[140:143], v[208:211], 0
	v_mfma_f32_16x16x32_bf16 v[64:67], v[136:139], v[152:155], v[64:67]
	v_mfma_f32_16x16x32_bf16 v[60:63], v[144:147], v[152:155], v[60:63]
	v_mfma_f32_16x16x32_bf16 v[56:59], v[136:139], v[160:163], v[56:59]
	v_mfma_f32_16x16x32_bf16 v[48:51], v[144:147], v[160:163], v[48:51]
	v_mfma_f32_16x16x32_bf16 v[40:43], v[136:139], v[200:203], v[40:43]
	v_mfma_f32_16x16x32_bf16 v[32:35], v[144:147], v[200:203], v[32:35]
	s_setprio 2
	s_barrier
; #define PG8_STAGE(bufoff, gbase, voff) do { _Pragma("unroll") for (int _i = 0; _i < 2; ++_i) \
;     __builtin_amdgcn_global_load_lds((const unsigned*)((const char*)(gbase) + (voff)[_i]), (LAS unsigned*)(lds + (bufoff) + ldsw + _i * 8192), 16, 0, 0); } while (0)
; #define PG8_LDA(dst, b, h) do { _Pragma("unroll") for (int m = 0; m < 4; ++m) _Pragma("unroll") for (int k = 0; k < 2; ++k) dst[m][k] = *(const LAS bf16x8*)(lds + PG8_SA(b, h) + aoff + m * 2048 + k * 1024); } while (0)
; #define PG8_LDB(dst, b, h) do { _Pragma("unroll") for (int n = 0; n < 2; ++n) _Pragma("unroll") for (int k = 0; k < 2; ++k) dst[n][k] = *(const LAS bf16x8*)(lds + PG8_SB(b, h) + boff + n * 2048 + k * 1024); } while (0)
; #define PG8_MMA(ai, bj, At, Bt) do { __builtin_amdgcn_s_setprio(1); _Pragma("unroll") for (int m = 0; m < 4; ++m) _Pragma("unroll") for (int n = 0; n < 2; ++n) _Pragma("unroll") for (int k = 0; k < 2; ++k) \
;     acc[ai][bj][m][n] = __builtin_amdgcn_mfma_f32_16x16x32_bf16(Bt[n][k], At[m][k], acc[ai][bj][m][n], 0, 0, 0); __builtin_amdgcn_s_setprio(0); } while (0)
; #define PG8_WAIT_V(n) asm volatile("s_waitcnt vmcnt(" #n ")" ::: "memory")
; #define PG8_WAIT_L(n) asm volatile("s_waitcnt lgkmcnt(" #n ")" ::: "memory")
; #define PG8_BAR __builtin_amdgcn_s_barrier()
; #define PG8_SCHED __builtin_amdgcn_sched_barrier(0)
; template <class Epi>
; DI void gemm_phase(LAS unsigned char* lds, const Gemm g, const Epi& E) {
;     ...
;       PG8_BAR; PG8_WAIT_L(0); PG8_MMA(1, 0, At, B0); PG8_BAR; PG8_SCHED;
;       PG8_STAGE(PG8_SB(0, 1), b2 + hstepB, voffB);
;       PG8_WAIT_V(6); PG8_BAR; PG8_MMA(1, 1, At, B1); PG8_BAR;
;       PG8_LDB(B0, 1, 0); PG8_SCHED; PG8_LDA(At, 1, 0); PG8_STAGE(PG8_SA(0, 1), a2 + hstepA, voffA);
;       PG8_WAIT_L(8); PG8_BAR; PG8_WAIT_L(0); PG8_MMA(0, 0, At, B0); PG8_BAR; PG8_SCHED;
;       PG8_LDB(B1, 1, 1); PG8_STAGE(PG8_SB(1, 0), b3, voffB);
;       PG8_BAR; PG8_WAIT_L(0); PG8_MMA(0, 1, At, B1); PG8_BAR;
	v_mfma_f32_16x16x32_bf16 v[24:27], v[136:139], v[212:215], v[24:27]
	v_mfma_f32_16x16x32_bf16 v[16:19], v[144:147], v[212:215], v[16:19]
	s_setprio 0
	ds_read_b128 v[132:135], v248 offset:32768
	ds_read_b128 v[136:139], v248 offset:33792
	ds_read_b128 v[140:143], v248 offset:34816
	ds_read_b128 v[144:147], v248 offset:35840
	s_add_u32 s56, s56, s18
	s_addc_u32 s57, s57, s19
	s_add_i32 s79, s80, s63
	v_lshl_add_u64 v[238:239], s[56:57], 0, v[2:3]
	s_mov_b32 m0, s79
	v_lshl_add_u64 v[240:241], s[56:57], 0, v[184:185]
	global_load_lds_dwordx4 v[238:239], off
	s_add_i32 m0, s79, 0x2000
	s_nop 0
	global_load_lds_dwordx4 v[240:241], off
	s_waitcnt vmcnt(6)
	s_barrier
	s_setprio 1
	v_mfma_f32_16x16x32_bf16 v[52:55], v[216:219], v[148:151], 0
	v_mfma_f32_16x16x32_bf16 v[44:47], v[224:227], v[148:151], 0
	v_mfma_f32_16x16x32_bf16 v[36:39], v[216:219], v[156:159], 0
	v_mfma_f32_16x16x32_bf16 v[28:31], v[224:227], v[156:159], 0
	v_mfma_f32_16x16x32_bf16 v[20:23], v[216:219], v[196:199], 0
	v_mfma_f32_16x16x32_bf16 v[12:15], v[224:227], v[196:199], 0
	v_mfma_f32_16x16x32_bf16 v[8:11], v[216:219], v[208:211], 0
	v_mfma_f32_16x16x32_bf16 v[4:7], v[224:227], v[208:211], 0
	v_mfma_f32_16x16x32_bf16 v[52:55], v[220:223], v[152:155], v[52:55]
	v_mfma_f32_16x16x32_bf16 v[44:47], v[228:231], v[152:155], v[44:47]
	v_mfma_f32_16x16x32_bf16 v[36:39], v[220:223], v[160:163], v[36:39]
	v_mfma_f32_16x16x32_bf16 v[28:31], v[228:231], v[160:163], v[28:31]
	v_mfma_f32_16x16x32_bf16 v[20:23], v[220:223], v[200:203], v[20:23]
	v_mfma_f32_16x16x32_bf16 v[12:15], v[228:231], v[200:203], v[12:15]
	s_setprio 2
	s_barrier
	v_mfma_f32_16x16x32_bf16 v[8:11], v[220:223], v[212:215], v[8:11]
	v_mfma_f32_16x16x32_bf16 v[4:7], v[228:231], v[212:215], v[4:7]
	s_setprio 0
	s_add_i32 s56, 0, 0x18000
	s_add_u32 s44, s44, s8
	s_addc_u32 s45, s45, 0
	s_mov_b32 m0, s66
	ds_read_b128 v[148:151], v195 offset:32768
	ds_read_b128 v[152:155], v195 offset:33792
	ds_read_b128 v[156:159], v195 offset:34816
	ds_read_b128 v[160:163], v195 offset:35840
	ds_read_b128 v[196:199], v195 offset:36864
	ds_read_b128 v[200:203], v195 offset:37888
	ds_read_b128 v[208:211], v195 offset:38912
	ds_read_b128 v[212:215], v195 offset:39936
	global_load_lds_dwordx4 v180, s[44:45]
	s_mov_b32 m0, s67
	s_nop 0
	global_load_lds_dwordx4 v182, s[44:45]
	s_waitcnt lgkmcnt(8)
	s_barrier
	s_waitcnt lgkmcnt(0)
	s_setprio 1
	s_waitcnt lgkmcnt(0)
	v_mfma_f32_16x16x32_bf16 v[128:131], v[132:135], v[148:151], v[128:131]
	v_mfma_f32_16x16x32_bf16 v[124:127], v[140:143], v[148:151], v[124:127]
	v_mfma_f32_16x16x32_bf16 v[116:119], v[132:135], v[156:159], v[116:119]
	v_mfma_f32_16x16x32_bf16 v[108:111], v[140:143], v[156:159], v[108:111]
	v_mfma_f32_16x16x32_bf16 v[100:103], v[132:135], v[196:199], v[100:103]
	v_mfma_f32_16x16x32_bf16 v[92:95], v[140:143], v[196:199], v[92:95]
	v_mfma_f32_16x16x32_bf16 v[84:87], v[132:135], v[208:211], v[84:87]
	v_mfma_f32_16x16x32_bf16 v[76:79], v[140:143], v[208:211], v[76:79]
	v_mfma_f32_16x16x32_bf16 v[128:131], v[136:139], v[152:155], v[128:131]
	v_mfma_f32_16x16x32_bf16 v[124:127], v[144:147], v[152:155], v[124:127]
	v_mfma_f32_16x16x32_bf16 v[116:119], v[136:139], v[160:163], v[116:119]
	v_mfma_f32_16x16x32_bf16 v[108:111], v[144:147], v[160:163], v[108:111]
	v_mfma_f32_16x16x32_bf16 v[100:103], v[136:139], v[200:203], v[100:103]
	v_mfma_f32_16x16x32_bf16 v[92:95], v[144:147], v[200:203], v[92:95]
	s_setprio 2
	s_barrier
	v_mfma_f32_16x16x32_bf16 v[84:87], v[136:139], v[212:215], v[84:87]
	v_mfma_f32_16x16x32_bf16 v[76:79], v[144:147], v[212:215], v[76:79]
	s_setprio 0
	s_add_i32 s44, 0, 0x1c000
	s_add_i32 s45, s56, s63
	v_lshl_add_u64 v[190:191], v[190:191], 0, s[84:85]
	s_mov_b32 m0, s45
	ds_read_b128 v[216:219], v248 offset:49152
	ds_read_b128 v[220:223], v248 offset:50176
	ds_read_b128 v[224:227], v248 offset:51200
	ds_read_b128 v[228:231], v248 offset:52224
	global_load_lds_dwordx4 v[190:191], off
	v_lshl_add_u64 v[190:191], v[232:233], 0, s[84:85]
	s_add_i32 m0, s45, 0x2000
	s_nop 0
	global_load_lds_dwordx4 v[190:191], off
	s_barrier
; #define PG8_STAGE(bufoff, gbase, voff) do { _Pragma("unroll") for (int _i = 0; _i < 2; ++_i) \
;     __builtin_amdgcn_global_load_lds((const unsigned*)((const char*)(gbase) + (voff)[_i]), (LAS unsigned*)(lds + (bufoff) + ldsw + _i * 8192), 16, 0, 0); } while (0)
; #define PG8_LDA(dst, b, h) do { _Pragma("unroll") for (int m = 0; m < 4; ++m) _Pragma("unroll") for (int k = 0; k < 2; ++k) dst[m][k] = *(const LAS bf16x8*)(lds + PG8_SA(b, h) + aoff + m * 2048 + k * 1024); } while (0)
; #define PG8_MMA(ai, bj, At, Bt) do { __builtin_amdgcn_s_setprio(1); _Pragma("unroll") for (int m = 0; m < 4; ++m) _Pragma("unroll") for (int n = 0; n < 2; ++n) _Pragma("unroll") for (int k = 0; k < 2; ++k) \
;     acc[ai][bj][m][n] = __builtin_amdgcn_mfma_f32_16x16x32_bf16(Bt[n][k], At[m][k], acc[ai][bj][m][n], 0, 0, 0); __builtin_amdgcn_s_setprio(0); } while (0)
; #define PG8_WAIT_V(n) asm volatile("s_waitcnt vmcnt(" #n ")" ::: "memory")
; #define PG8_WAIT_L(n) asm volatile("s_waitcnt lgkmcnt(" #n ")" ::: "memory")
; #define PG8_BAR __builtin_amdgcn_s_barrier()
; #define PG8_SCHED __builtin_amdgcn_sched_barrier(0)
; template <class Epi>
; DI void gemm_phase(LAS unsigned char* lds, const Gemm g, const Epi& E) {
;     ...
;       PG8_BAR; PG8_WAIT_L(0); PG8_MMA(0, 1, At, B1); PG8_BAR;
;       PG8_LDA(At, 1, 1); PG8_STAGE(PG8_SA(1, 0), a3, voffA);
;       PG8_BAR; PG8_WAIT_L(0); PG8_MMA(1, 0, At, B0); PG8_BAR; PG8_SCHED;
;       PG8_STAGE(PG8_SB(1, 1), b3 + hstepB, voffB);
;       PG8_WAIT_V(6); PG8_BAR; PG8_MMA(1, 1, At, B1); PG8_BAR;
	s_waitcnt lgkmcnt(0)
	s_setprio 1
	s_waitcnt lgkmcnt(0)
	v_mfma_f32_16x16x32_bf16 v[120:123], v[216:219], v[148:151], v[120:123]
	v_mfma_f32_16x16x32_bf16 v[112:115], v[224:227], v[148:151], v[112:115]
	v_mfma_f32_16x16x32_bf16 v[104:107], v[216:219], v[156:159], v[104:107]
	v_mfma_f32_16x16x32_bf16 v[96:99], v[224:227], v[156:159], v[96:99]
	v_mfma_f32_16x16x32_bf16 v[88:91], v[216:219], v[196:199], v[88:91]
	v_mfma_f32_16x16x32_bf16 v[80:83], v[224:227], v[196:199], v[80:83]
	v_mfma_f32_16x16x32_bf16 v[72:75], v[216:219], v[208:211], v[72:75]
	v_mfma_f32_16x16x32_bf16 v[68:71], v[224:227], v[208:211], v[68:71]
	v_mfma_f32_16x16x32_bf16 v[120:123], v[220:223], v[152:155], v[120:123]
	v_mfma_f32_16x16x32_bf16 v[112:115], v[228:231], v[152:155], v[112:115]
	v_mfma_f32_16x16x32_bf16 v[104:107], v[220:223], v[160:163], v[104:107]
	v_mfma_f32_16x16x32_bf16 v[96:99], v[228:231], v[160:163], v[96:99]
	v_mfma_f32_16x16x32_bf16 v[88:91], v[220:223], v[200:203], v[88:91]
	v_mfma_f32_16x16x32_bf16 v[80:83], v[228:231], v[200:203], v[80:83]
	s_setprio 2
	s_barrier
	v_mfma_f32_16x16x32_bf16 v[72:75], v[220:223], v[212:215], v[72:75]
	v_mfma_f32_16x16x32_bf16 v[68:71], v[228:231], v[212:215], v[68:71]
	s_setprio 0
	s_mov_b32 m0, s69
	v_lshl_add_u64 v[190:191], v[234:235], 0, s[84:85]
	ds_read_b128 v[148:151], v195 offset:49152
	ds_read_b128 v[152:155], v195 offset:50176
	ds_read_b128 v[156:159], v195 offset:51200
	ds_read_b128 v[160:163], v195 offset:52224
	ds_read_b128 v[196:199], v195 offset:53248
	ds_read_b128 v[200:203], v195 offset:54272
	ds_read_b128 v[208:211], v195 offset:55296
	ds_read_b128 v[212:215], v195 offset:56320
	global_load_lds_dwordx4 v[190:191], off
	v_lshl_add_u64 v[190:191], v[236:237], 0, s[84:85]
	s_mov_b32 m0, s71
	s_nop 0
	global_load_lds_dwordx4 v[190:191], off
	s_waitcnt vmcnt(10)
	s_barrier
	s_waitcnt lgkmcnt(0)
	s_setprio 1
	s_waitcnt lgkmcnt(0)
	v_mfma_f32_16x16x32_bf16 v[64:67], v[132:135], v[148:151], v[64:67]
	v_mfma_f32_16x16x32_bf16 v[60:63], v[140:143], v[148:151], v[60:63]
	v_mfma_f32_16x16x32_bf16 v[56:59], v[132:135], v[156:159], v[56:59]
	v_mfma_f32_16x16x32_bf16 v[48:51], v[140:143], v[156:159], v[48:51]
	v_mfma_f32_16x16x32_bf16 v[40:43], v[132:135], v[196:199], v[40:43]
	v_mfma_f32_16x16x32_bf16 v[32:35], v[140:143], v[196:199], v[32:35]
	v_mfma_f32_16x16x32_bf16 v[24:27], v[132:135], v[208:211], v[24:27]
	v_mfma_f32_16x16x32_bf16 v[16:19], v[140:143], v[208:211], v[16:19]
	v_mfma_f32_16x16x32_bf16 v[64:67], v[136:139], v[152:155], v[64:67]
	v_mfma_f32_16x16x32_bf16 v[60:63], v[144:147], v[152:155], v[60:63]
	v_mfma_f32_16x16x32_bf16 v[56:59], v[136:139], v[160:163], v[56:59]
	v_mfma_f32_16x16x32_bf16 v[48:51], v[144:147], v[160:163], v[48:51]
	v_mfma_f32_16x16x32_bf16 v[40:43], v[136:139], v[200:203], v[40:43]
	v_mfma_f32_16x16x32_bf16 v[32:35], v[144:147], v[200:203], v[32:35]
	s_setprio 2
	s_barrier
	v_mfma_f32_16x16x32_bf16 v[24:27], v[136:139], v[212:215], v[24:27]
	v_mfma_f32_16x16x32_bf16 v[16:19], v[144:147], v[212:215], v[16:19]
	s_setprio 0
	ds_read_b128 v[132:135], v248
	ds_read_b128 v[136:139], v248 offset:1024
	ds_read_b128 v[140:143], v248 offset:2048
	ds_read_b128 v[144:147], v248 offset:3072
	s_add_i32 s44, s44, s63
	v_lshl_add_u64 v[246:247], v[238:239], 0, s[84:85]
	s_mov_b32 m0, s44
	s_nop 0
	global_load_lds_dwordx4 v[246:247], off
	v_lshl_add_u64 v[246:247], v[240:241], 0, s[84:85]
	s_add_i32 m0, s44, 0x2000
	s_nop 0
	global_load_lds_dwordx4 v[246:247], off
	s_waitcnt vmcnt(6)
	s_barrier
	s_setprio 1
	v_mfma_f32_16x16x32_bf16 v[52:55], v[216:219], v[148:151], v[52:55]
	v_mfma_f32_16x16x32_bf16 v[44:47], v[224:227], v[148:151], v[44:47]
	v_mfma_f32_16x16x32_bf16 v[36:39], v[216:219], v[156:159], v[36:39]
	v_mfma_f32_16x16x32_bf16 v[28:31], v[224:227], v[156:159], v[28:31]
	v_mfma_f32_16x16x32_bf16 v[20:23], v[216:219], v[196:199], v[20:23]
	v_mfma_f32_16x16x32_bf16 v[12:15], v[224:227], v[196:199], v[12:15]
	v_mfma_f32_16x16x32_bf16 v[8:11], v[216:219], v[208:211], v[8:11]
	v_mfma_f32_16x16x32_bf16 v[4:7], v[224:227], v[208:211], v[4:7]
	v_mfma_f32_16x16x32_bf16 v[52:55], v[220:223], v[152:155], v[52:55]
	v_mfma_f32_16x16x32_bf16 v[44:47], v[228:231], v[152:155], v[44:47]
	v_mfma_f32_16x16x32_bf16 v[36:39], v[220:223], v[160:163], v[36:39]
	v_mfma_f32_16x16x32_bf16 v[28:31], v[228:231], v[160:163], v[28:31]
	v_mfma_f32_16x16x32_bf16 v[20:23], v[220:223], v[200:203], v[20:23]
	v_mfma_f32_16x16x32_bf16 v[12:15], v[228:231], v[200:203], v[12:15]
	s_setprio 2
	s_barrier
	v_mfma_f32_16x16x32_bf16 v[8:11], v[220:223], v[212:215], v[8:11]
	v_mfma_f32_16x16x32_bf16 v[4:7], v[228:231], v[212:215], v[4:7]
	s_setprio 0
	s_add_u32 s42, s42, 0x100
	s_addc_u32 s43, s43, 0
	s_add_u32 s58, s58, 0x100
	s_addc_u32 s59, s59, 0
	s_cmp_ge_u32 s78, s68
	s_mov_b32 s44, s78
	s_cbranch_scc1 .Lpeel_exit_514

;   DI void operator()(const f32x4 (&acc)[2][2][4][2], const Unit& u, int wr, int wc, int fr, int fq) const {
;     const int row0 = u.pm * BM + wr * 64 + fr, col0 = u.pn * BM + wc * 32 + 8 * fq;
;     f32x4 bv[2][2], sv[2][2];
; #pragma unroll
;     for (int bj = 0; bj < 2; ++bj)
; #pragma unroll
;       for (int n = 0; n < 2; ++n) {
;         bv[bj][n] = bias ? *(const f32x4*)(bias + col0 + bj * HALF + 4 * n) : (f32x4){0.f, 0.f, 0.f, 0.f};
;         sv[bj][n] = scale ? *(const f32x4*)(scale + col0 + bj * HALF + 4 * n) : (f32x4){1.f, 1.f, 1.f, 1.f};
;       }
.Lpeel_exit_514:
	s_waitcnt lgkmcnt(0)
	v_lshl_or_b32 v190, s77, 8, v194
	v_ashrrev_i32_e32 v191, 31, v190
	v_cndmask_b32_e64 v132, 0, 1, s[36:37]
	v_cmp_ne_u32_e64 s[42:43], 1, v132
	s_andn2_b64 vcc, exec, s[36:37]
	v_lshl_add_u64 v[156:157], v[190:191], 2, s[48:49]
	s_cbranch_vccnz .LBB0_517
	global_load_dwordx4 v[132:135], v[156:157], off
	s_branch .LBB0_518
